# GEMM main loops: scalar set-up of the two 12-read load segments moved to the tail of the wave's previous light load segment (first trip's copy ahead of the loop)
# speedup vs baseline: 1.0103x; 1.0103x over previous
.LBB0_226:
	s_ashr_i32 s35, s34, 31
	s_lshl_b64 s[6:7], s[34:35], 20
	v_cmp_lt_i64_e32 vcc, s[38:39], v[156:157]
	s_add_u32 s38, s15, s6
	s_addc_u32 s39, s30, s7
	s_and_b64 s[6:7], vcc, exec
	s_cselect_b32 s5, s39, s21
	s_cselect_b32 s6, s38, s20
	s_ashr_i32 s25, s24, 31
	s_lshl_b64 s[42:43], s[24:25], 20
	s_add_u32 s44, s46, s42
	s_addc_u32 s45, s47, s43
	s_and_b64 s[42:43], vcc, exec
	s_cselect_b32 s7, s45, s23
	s_cselect_b32 s25, s44, s22
	s_add_u32 s20, s20, 0x80080
	s_addc_u32 s21, s21, 0
	s_add_u32 s35, s22, 0x100
	v_mov_b32_e32 v0, 0
	s_addc_u32 s57, s23, 0
	s_mov_b32 s58, -2
	v_mov_b32_e32 v1, v0
	v_mov_b32_e32 v2, v0
	v_mov_b32_e32 v3, v0
	v_mov_b32_e32 v4, v0
	v_mov_b32_e32 v5, v0
	v_mov_b32_e32 v6, v0
	v_mov_b32_e32 v7, v0
	v_mov_b32_e32 v12, v0
	v_mov_b32_e32 v13, v0
	v_mov_b32_e32 v14, v0
	v_mov_b32_e32 v15, v0
	v_mov_b32_e32 v20, v0
	v_mov_b32_e32 v21, v0
	v_mov_b32_e32 v22, v0
	v_mov_b32_e32 v23, v0
	v_mov_b32_e32 v28, v0
	v_mov_b32_e32 v29, v0
	v_mov_b32_e32 v30, v0
	v_mov_b32_e32 v31, v0
	v_mov_b32_e32 v36, v0
	v_mov_b32_e32 v37, v0
	v_mov_b32_e32 v38, v0
	v_mov_b32_e32 v39, v0
	v_mov_b32_e32 v44, v0
	v_mov_b32_e32 v45, v0
	v_mov_b32_e32 v46, v0
	v_mov_b32_e32 v47, v0
	v_mov_b32_e32 v52, v0
	v_mov_b32_e32 v53, v0
	v_mov_b32_e32 v54, v0
	v_mov_b32_e32 v55, v0
	v_mov_b32_e32 v8, v0
	v_mov_b32_e32 v9, v0
	v_mov_b32_e32 v10, v0
	v_mov_b32_e32 v11, v0
	v_mov_b32_e32 v16, v0
	v_mov_b32_e32 v17, v0
	v_mov_b32_e32 v18, v0
	v_mov_b32_e32 v19, v0
	v_mov_b32_e32 v24, v0
	v_mov_b32_e32 v25, v0
	v_mov_b32_e32 v26, v0
	v_mov_b32_e32 v27, v0
	v_mov_b32_e32 v32, v0
	v_mov_b32_e32 v33, v0
	v_mov_b32_e32 v34, v0
	v_mov_b32_e32 v35, v0
	v_mov_b32_e32 v40, v0
	v_mov_b32_e32 v41, v0
	v_mov_b32_e32 v42, v0
	v_mov_b32_e32 v43, v0
	v_mov_b32_e32 v48, v0
	v_mov_b32_e32 v49, v0
	v_mov_b32_e32 v50, v0
	v_mov_b32_e32 v51, v0
	v_mov_b32_e32 v56, v0
	v_mov_b32_e32 v57, v0
	v_mov_b32_e32 v58, v0
	v_mov_b32_e32 v59, v0
	v_mov_b32_e32 v60, v0
	v_mov_b32_e32 v61, v0
	v_mov_b32_e32 v62, v0
	v_mov_b32_e32 v63, v0
	v_mov_b32_e32 v64, v0
	v_mov_b32_e32 v65, v0
	v_mov_b32_e32 v66, v0
	v_mov_b32_e32 v67, v0
	v_mov_b32_e32 v68, v0
	v_mov_b32_e32 v69, v0
	v_mov_b32_e32 v70, v0
	v_mov_b32_e32 v71, v0
	v_mov_b32_e32 v80, v0
	v_mov_b32_e32 v81, v0
	v_mov_b32_e32 v82, v0
	v_mov_b32_e32 v83, v0
	v_mov_b32_e32 v84, v0
	v_mov_b32_e32 v85, v0
	v_mov_b32_e32 v86, v0
	v_mov_b32_e32 v87, v0
	v_mov_b32_e32 v96, v0
	v_mov_b32_e32 v97, v0
	v_mov_b32_e32 v98, v0
	v_mov_b32_e32 v99, v0
	v_mov_b32_e32 v100, v0
	v_mov_b32_e32 v101, v0
	v_mov_b32_e32 v102, v0
	v_mov_b32_e32 v103, v0
	v_mov_b32_e32 v112, v0
	v_mov_b32_e32 v113, v0
	v_mov_b32_e32 v114, v0
	v_mov_b32_e32 v115, v0
	v_mov_b32_e32 v116, v0
	v_mov_b32_e32 v117, v0
	v_mov_b32_e32 v118, v0
	v_mov_b32_e32 v119, v0
	v_mov_b32_e32 v72, v0
	v_mov_b32_e32 v73, v0
	v_mov_b32_e32 v74, v0
	v_mov_b32_e32 v75, v0
	v_mov_b32_e32 v76, v0
	v_mov_b32_e32 v77, v0
	v_mov_b32_e32 v78, v0
	v_mov_b32_e32 v79, v0
	v_mov_b32_e32 v88, v0
	v_mov_b32_e32 v89, v0
	v_mov_b32_e32 v90, v0
	v_mov_b32_e32 v91, v0
	v_mov_b32_e32 v92, v0
	v_mov_b32_e32 v93, v0
	v_mov_b32_e32 v94, v0
	v_mov_b32_e32 v95, v0
	v_mov_b32_e32 v104, v0
	v_mov_b32_e32 v105, v0
	v_mov_b32_e32 v106, v0
	v_mov_b32_e32 v107, v0
	v_mov_b32_e32 v108, v0
	v_mov_b32_e32 v109, v0
	v_mov_b32_e32 v110, v0
	v_mov_b32_e32 v111, v0
	v_mov_b32_e32 v120, v0
	v_mov_b32_e32 v121, v0
	v_mov_b32_e32 v122, v0
	v_mov_b32_e32 v123, v0
	v_mov_b32_e32 v124, v0
	v_mov_b32_e32 v125, v0
	v_mov_b32_e32 v126, v0
	v_mov_b32_e32 v127, v0
	v_add_u32_e32 v234, 0x10000, v165
	v_add_u32_e32 v235, 0x14000, v165
	v_add_u32_e32 v236, 0x18000, v165
	v_add_u32_e32 v237, 0x1c000, v165
	s_add_u32 s22, s20, 0xfff80080
	s_addc_u32 s23, s21, -1
	s_add_i32 s59, 0, 0x10000
	s_cmp_eq_u32 s58, 28
	s_cselect_b32 s43, s5, s23
	s_cselect_b32 s42, s6, s22
	s_cselect_b32 s23, s7, s57
	s_cselect_b32 s22, s25, s35
	s_add_i32 m0, s49, 0xc000
.LBB0_227:
	ds_read_b128 v[140:143], v234
	ds_read_b128 v[144:147], v234 offset:1024
	ds_read_b128 v[148:151], v234 offset:2048
	ds_read_b128 v[170:173], v234 offset:3072
	ds_read_b128 v[174:177], v168
	ds_read_b128 v[178:181], v168 offset:1024
	ds_read_b128 v[182:185], v168 offset:2048
	ds_read_b128 v[186:189], v168 offset:3072
	ds_read_b128 v[190:193], v168 offset:4096
	ds_read_b128 v[206:209], v168 offset:5120
	ds_read_b128 v[210:213], v168 offset:6144
	ds_read_b128 v[214:217], v168 offset:7168
	global_load_lds_dwordx4 v136, s[20:21]
	s_add_i32 m0, s49, 0xe000
	s_nop 0
	global_load_lds_dwordx4 v138, s[20:21]
	s_waitcnt lgkmcnt(8)
	s_barrier
	s_waitcnt lgkmcnt(0)
	v_mfma_f32_16x16x32_bf16 v[124:127], v[140:143], v[174:177], v[124:127]
	v_mfma_f32_16x16x32_bf16 v[120:123], v[148:151], v[174:177], v[120:123]
	v_mfma_f32_16x16x32_bf16 v[108:111], v[140:143], v[182:185], v[108:111]
	v_mfma_f32_16x16x32_bf16 v[104:107], v[148:151], v[182:185], v[104:107]
	v_mfma_f32_16x16x32_bf16 v[92:95], v[140:143], v[190:193], v[92:95]
	v_mfma_f32_16x16x32_bf16 v[88:91], v[148:151], v[190:193], v[88:91]
	v_mfma_f32_16x16x32_bf16 v[76:79], v[140:143], v[210:213], v[76:79]
	v_mfma_f32_16x16x32_bf16 v[72:75], v[148:151], v[210:213], v[72:75]
	v_mfma_f32_16x16x32_bf16 v[124:127], v[144:147], v[178:181], v[124:127]
	v_mfma_f32_16x16x32_bf16 v[120:123], v[170:173], v[178:181], v[120:123]
	v_mfma_f32_16x16x32_bf16 v[108:111], v[144:147], v[186:189], v[108:111]
	v_mfma_f32_16x16x32_bf16 v[104:107], v[170:173], v[186:189], v[104:107]
	v_mfma_f32_16x16x32_bf16 v[92:95], v[144:147], v[206:209], v[92:95]
	v_mfma_f32_16x16x32_bf16 v[88:91], v[170:173], v[206:209], v[88:91]
	v_mfma_f32_16x16x32_bf16 v[76:79], v[144:147], v[214:217], v[76:79]
	v_mfma_f32_16x16x32_bf16 v[72:75], v[170:173], v[214:217], v[72:75]
	s_barrier
	s_add_i32 s62, 0, 0x14000
	s_add_i32 s59, s59, s48
	s_mov_b32 m0, s59
	ds_read_b128 v[218:221], v235
	ds_read_b128 v[222:225], v235 offset:1024
	ds_read_b128 v[226:229], v235 offset:2048
	ds_read_b128 v[230:233], v235 offset:3072
	global_load_lds_dwordx4 v130, s[22:23]
	s_add_i32 m0, s59, 0x2000
	s_nop 0
	global_load_lds_dwordx4 v134, s[22:23]
	s_barrier
	s_waitcnt lgkmcnt(0)
	v_mfma_f32_16x16x32_bf16 v[116:119], v[218:221], v[174:177], v[116:119]
	v_mfma_f32_16x16x32_bf16 v[112:115], v[226:229], v[174:177], v[112:115]
	v_mfma_f32_16x16x32_bf16 v[100:103], v[218:221], v[182:185], v[100:103]
	v_mfma_f32_16x16x32_bf16 v[96:99], v[226:229], v[182:185], v[96:99]
	v_mfma_f32_16x16x32_bf16 v[84:87], v[218:221], v[190:193], v[84:87]
	v_mfma_f32_16x16x32_bf16 v[80:83], v[226:229], v[190:193], v[80:83]
	v_mfma_f32_16x16x32_bf16 v[68:71], v[218:221], v[210:213], v[68:71]
	v_mfma_f32_16x16x32_bf16 v[64:67], v[226:229], v[210:213], v[64:67]
	v_mfma_f32_16x16x32_bf16 v[116:119], v[222:225], v[178:181], v[116:119]
	v_mfma_f32_16x16x32_bf16 v[112:115], v[230:233], v[178:181], v[112:115]
	v_mfma_f32_16x16x32_bf16 v[100:103], v[222:225], v[186:189], v[100:103]
	v_mfma_f32_16x16x32_bf16 v[96:99], v[230:233], v[186:189], v[96:99]
	v_mfma_f32_16x16x32_bf16 v[84:87], v[222:225], v[206:209], v[84:87]
	v_mfma_f32_16x16x32_bf16 v[80:83], v[230:233], v[206:209], v[80:83]
	v_mfma_f32_16x16x32_bf16 v[68:71], v[222:225], v[214:217], v[68:71]
	v_mfma_f32_16x16x32_bf16 v[64:67], v[230:233], v[214:217], v[64:67]
	s_barrier
	s_mov_b32 m0, s49
	s_add_u32 s98, s42, 0x80
	s_addc_u32 s99, s43, 0
	ds_read_b128 v[174:177], v168 offset:16384
	ds_read_b128 v[178:181], v168 offset:17408
	ds_read_b128 v[182:185], v168 offset:18432
	ds_read_b128 v[186:189], v168 offset:19456
	ds_read_b128 v[190:193], v168 offset:20480
	ds_read_b128 v[206:209], v168 offset:21504
	ds_read_b128 v[210:213], v168 offset:22528
	ds_read_b128 v[214:217], v168 offset:23552
	global_load_lds_dwordx4 v128, s[42:43]
	s_mov_b32 m0, s50
	s_nop 0
	global_load_lds_dwordx4 v132, s[42:43]
	s_barrier
	s_waitcnt lgkmcnt(0)
	v_mfma_f32_16x16x32_bf16 v[60:63], v[140:143], v[174:177], v[60:63]
	v_mfma_f32_16x16x32_bf16 v[56:59], v[148:151], v[174:177], v[56:59]
	v_mfma_f32_16x16x32_bf16 v[48:51], v[140:143], v[182:185], v[48:51]
	v_mfma_f32_16x16x32_bf16 v[40:43], v[148:151], v[182:185], v[40:43]
	v_mfma_f32_16x16x32_bf16 v[32:35], v[140:143], v[190:193], v[32:35]
	v_mfma_f32_16x16x32_bf16 v[24:27], v[148:151], v[190:193], v[24:27]
	v_mfma_f32_16x16x32_bf16 v[16:19], v[140:143], v[210:213], v[16:19]
	v_mfma_f32_16x16x32_bf16 v[8:11], v[148:151], v[210:213], v[8:11]
	v_mfma_f32_16x16x32_bf16 v[60:63], v[144:147], v[178:181], v[60:63]
	v_mfma_f32_16x16x32_bf16 v[56:59], v[170:173], v[178:181], v[56:59]
	v_mfma_f32_16x16x32_bf16 v[48:51], v[144:147], v[186:189], v[48:51]
	v_mfma_f32_16x16x32_bf16 v[40:43], v[170:173], v[186:189], v[40:43]
	v_mfma_f32_16x16x32_bf16 v[32:35], v[144:147], v[206:209], v[32:35]
	v_mfma_f32_16x16x32_bf16 v[24:27], v[170:173], v[206:209], v[24:27]
	v_mfma_f32_16x16x32_bf16 v[16:19], v[144:147], v[214:217], v[16:19]
	v_mfma_f32_16x16x32_bf16 v[8:11], v[170:173], v[214:217], v[8:11]
	s_barrier
	s_add_u32 s60, s22, 0x80000
	s_addc_u32 s61, s23, 0
	s_add_i32 s59, s62, s48
	s_mov_b32 m0, s59
	s_nop 0
	global_load_lds_dwordx4 v130, s[60:61]
	s_add_i32 m0, s59, 0x2000
	s_nop 0
	global_load_lds_dwordx4 v134, s[60:61]
	s_add_i32 s59, 0, 0x18000
	s_add_u32 s42, s42, 0x80000
	s_addc_u32 s43, s43, 0
	s_mov_b32 m0, s51
	s_waitcnt vmcnt(6)
	s_barrier
	v_mfma_f32_16x16x32_bf16 v[52:55], v[218:221], v[174:177], v[52:55]
	v_mfma_f32_16x16x32_bf16 v[44:47], v[226:229], v[174:177], v[44:47]
	v_mfma_f32_16x16x32_bf16 v[36:39], v[218:221], v[182:185], v[36:39]
	v_mfma_f32_16x16x32_bf16 v[28:31], v[226:229], v[182:185], v[28:31]
	v_mfma_f32_16x16x32_bf16 v[20:23], v[218:221], v[190:193], v[20:23]
	v_mfma_f32_16x16x32_bf16 v[12:15], v[226:229], v[190:193], v[12:15]
	v_mfma_f32_16x16x32_bf16 v[4:7], v[218:221], v[210:213], v[4:7]
	v_mfma_f32_16x16x32_bf16 v[0:3], v[226:229], v[210:213], v[0:3]
	v_mfma_f32_16x16x32_bf16 v[52:55], v[222:225], v[178:181], v[52:55]
	v_mfma_f32_16x16x32_bf16 v[44:47], v[230:233], v[178:181], v[44:47]
	v_mfma_f32_16x16x32_bf16 v[36:39], v[222:225], v[186:189], v[36:39]
	v_mfma_f32_16x16x32_bf16 v[28:31], v[230:233], v[186:189], v[28:31]
	v_mfma_f32_16x16x32_bf16 v[20:23], v[222:225], v[206:209], v[20:23]
	v_mfma_f32_16x16x32_bf16 v[12:15], v[230:233], v[206:209], v[12:15]
	v_mfma_f32_16x16x32_bf16 v[4:7], v[222:225], v[214:217], v[4:7]
	v_mfma_f32_16x16x32_bf16 v[0:3], v[230:233], v[214:217], v[0:3]
	s_barrier
	ds_read_b128 v[140:143], v236
	ds_read_b128 v[144:147], v236 offset:1024
	ds_read_b128 v[148:151], v236 offset:2048
	ds_read_b128 v[170:173], v236 offset:3072
	ds_read_b128 v[174:177], v168 offset:32768
	ds_read_b128 v[178:181], v168 offset:33792
	ds_read_b128 v[182:185], v168 offset:34816
	ds_read_b128 v[186:189], v168 offset:35840
	ds_read_b128 v[190:193], v168 offset:36864
	ds_read_b128 v[206:209], v168 offset:37888
	ds_read_b128 v[210:213], v168 offset:38912
	ds_read_b128 v[214:217], v168 offset:39936
	global_load_lds_dwordx4 v128, s[42:43]
	s_mov_b32 m0, s52
	s_nop 0
	global_load_lds_dwordx4 v132, s[42:43]
	s_waitcnt lgkmcnt(8)
	s_barrier
	s_waitcnt lgkmcnt(0)
	v_mfma_f32_16x16x32_bf16 v[124:127], v[140:143], v[174:177], v[124:127]
	v_mfma_f32_16x16x32_bf16 v[120:123], v[148:151], v[174:177], v[120:123]
	v_mfma_f32_16x16x32_bf16 v[108:111], v[140:143], v[182:185], v[108:111]
	v_mfma_f32_16x16x32_bf16 v[104:107], v[148:151], v[182:185], v[104:107]
	v_mfma_f32_16x16x32_bf16 v[92:95], v[140:143], v[190:193], v[92:95]
	v_mfma_f32_16x16x32_bf16 v[88:91], v[148:151], v[190:193], v[88:91]
	v_mfma_f32_16x16x32_bf16 v[76:79], v[140:143], v[210:213], v[76:79]
	v_mfma_f32_16x16x32_bf16 v[72:75], v[148:151], v[210:213], v[72:75]
	v_mfma_f32_16x16x32_bf16 v[124:127], v[144:147], v[178:181], v[124:127]
	v_mfma_f32_16x16x32_bf16 v[120:123], v[170:173], v[178:181], v[120:123]
	v_mfma_f32_16x16x32_bf16 v[108:111], v[144:147], v[186:189], v[108:111]
	v_mfma_f32_16x16x32_bf16 v[104:107], v[170:173], v[186:189], v[104:107]
	v_mfma_f32_16x16x32_bf16 v[92:95], v[144:147], v[206:209], v[92:95]
	v_mfma_f32_16x16x32_bf16 v[88:91], v[170:173], v[206:209], v[88:91]
	v_mfma_f32_16x16x32_bf16 v[76:79], v[144:147], v[214:217], v[76:79]
	v_mfma_f32_16x16x32_bf16 v[72:75], v[170:173], v[214:217], v[72:75]
	s_barrier
	s_add_i32 s42, 0, 0x1c000
	s_add_i32 s43, s59, s48
	s_add_u32 s100, s22, 0x80
	s_addc_u32 s101, s23, 0
	s_mov_b32 m0, s43
	ds_read_b128 v[218:221], v237
	ds_read_b128 v[222:225], v237 offset:1024
	ds_read_b128 v[226:229], v237 offset:2048
	ds_read_b128 v[230:233], v237 offset:3072
	global_load_lds_dwordx4 v130, s[100:101]
	s_add_i32 m0, s43, 0x2000
	s_nop 0
	global_load_lds_dwordx4 v134, s[100:101]
	s_barrier
	s_waitcnt lgkmcnt(0)
	v_mfma_f32_16x16x32_bf16 v[116:119], v[218:221], v[174:177], v[116:119]
	v_mfma_f32_16x16x32_bf16 v[112:115], v[226:229], v[174:177], v[112:115]
	v_mfma_f32_16x16x32_bf16 v[100:103], v[218:221], v[182:185], v[100:103]
	v_mfma_f32_16x16x32_bf16 v[96:99], v[226:229], v[182:185], v[96:99]
	v_mfma_f32_16x16x32_bf16 v[84:87], v[218:221], v[190:193], v[84:87]
	v_mfma_f32_16x16x32_bf16 v[80:83], v[226:229], v[190:193], v[80:83]
	v_mfma_f32_16x16x32_bf16 v[68:71], v[218:221], v[210:213], v[68:71]
	v_mfma_f32_16x16x32_bf16 v[64:67], v[226:229], v[210:213], v[64:67]
	v_mfma_f32_16x16x32_bf16 v[116:119], v[222:225], v[178:181], v[116:119]
	v_mfma_f32_16x16x32_bf16 v[112:115], v[230:233], v[178:181], v[112:115]
	v_mfma_f32_16x16x32_bf16 v[100:103], v[222:225], v[186:189], v[100:103]
	v_mfma_f32_16x16x32_bf16 v[96:99], v[230:233], v[186:189], v[96:99]
	v_mfma_f32_16x16x32_bf16 v[84:87], v[222:225], v[206:209], v[84:87]
	v_mfma_f32_16x16x32_bf16 v[80:83], v[230:233], v[206:209], v[80:83]
	v_mfma_f32_16x16x32_bf16 v[68:71], v[222:225], v[214:217], v[68:71]
	v_mfma_f32_16x16x32_bf16 v[64:67], v[230:233], v[214:217], v[64:67]
	s_barrier
	s_mov_b32 m0, s53
	ds_read_b128 v[174:177], v168 offset:49152
	ds_read_b128 v[178:181], v168 offset:50176
	ds_read_b128 v[182:185], v168 offset:51200
	ds_read_b128 v[186:189], v168 offset:52224
	ds_read_b128 v[190:193], v168 offset:53248
	ds_read_b128 v[206:209], v168 offset:54272
	ds_read_b128 v[210:213], v168 offset:55296
	ds_read_b128 v[214:217], v168 offset:56320
	global_load_lds_dwordx4 v128, s[98:99]
	s_mov_b32 m0, s54
	s_nop 0
	global_load_lds_dwordx4 v132, s[98:99]
	s_barrier
	s_waitcnt lgkmcnt(0)
	v_mfma_f32_16x16x32_bf16 v[60:63], v[140:143], v[174:177], v[60:63]
	v_mfma_f32_16x16x32_bf16 v[56:59], v[148:151], v[174:177], v[56:59]
	v_mfma_f32_16x16x32_bf16 v[48:51], v[140:143], v[182:185], v[48:51]
	v_mfma_f32_16x16x32_bf16 v[40:43], v[148:151], v[182:185], v[40:43]
	v_mfma_f32_16x16x32_bf16 v[32:35], v[140:143], v[190:193], v[32:35]
	v_mfma_f32_16x16x32_bf16 v[24:27], v[148:151], v[190:193], v[24:27]
	v_mfma_f32_16x16x32_bf16 v[16:19], v[140:143], v[210:213], v[16:19]
	v_mfma_f32_16x16x32_bf16 v[8:11], v[148:151], v[210:213], v[8:11]
	v_mfma_f32_16x16x32_bf16 v[60:63], v[144:147], v[178:181], v[60:63]
	v_mfma_f32_16x16x32_bf16 v[56:59], v[170:173], v[178:181], v[56:59]
	v_mfma_f32_16x16x32_bf16 v[48:51], v[144:147], v[186:189], v[48:51]
	v_mfma_f32_16x16x32_bf16 v[40:43], v[170:173], v[186:189], v[40:43]
	v_mfma_f32_16x16x32_bf16 v[32:35], v[144:147], v[206:209], v[32:35]
	v_mfma_f32_16x16x32_bf16 v[24:27], v[170:173], v[206:209], v[24:27]
	v_mfma_f32_16x16x32_bf16 v[16:19], v[144:147], v[214:217], v[16:19]
	v_mfma_f32_16x16x32_bf16 v[8:11], v[170:173], v[214:217], v[8:11]
	s_barrier
	s_add_u32 s22, s22, 0x80080
	s_addc_u32 s23, s23, 0
	s_add_i32 s42, s42, s48
	s_mov_b32 m0, s42
	s_nop 0
	global_load_lds_dwordx4 v130, s[22:23]
	s_add_i32 m0, s42, 0x2000
	s_nop 0
	global_load_lds_dwordx4 v134, s[22:23]
	s_add_i32 s58, s58, 2
	s_add_u32 s20, s20, 0x100
	s_addc_u32 s21, s21, 0
	s_add_u32 s35, s35, 0x100
	s_addc_u32 s57, s57, 0
	s_add_u32 s22, s20, 0xfff80080
	s_addc_u32 s23, s21, -1
	s_add_i32 s59, 0, 0x10000
	s_cmp_eq_u32 s58, 28
	s_cselect_b32 s43, s5, s23
	s_cselect_b32 s42, s6, s22
	s_cselect_b32 s23, s7, s57
	s_cselect_b32 s22, s25, s35
	s_add_i32 m0, s49, 0xc000
	s_cmp_gt_u32 s58, 29
	s_waitcnt vmcnt(6)
	s_barrier
	v_mfma_f32_16x16x32_bf16 v[52:55], v[218:221], v[174:177], v[52:55]
	v_mfma_f32_16x16x32_bf16 v[44:47], v[226:229], v[174:177], v[44:47]
	v_mfma_f32_16x16x32_bf16 v[36:39], v[218:221], v[182:185], v[36:39]
	v_mfma_f32_16x16x32_bf16 v[28:31], v[226:229], v[182:185], v[28:31]
	v_mfma_f32_16x16x32_bf16 v[20:23], v[218:221], v[190:193], v[20:23]
	v_mfma_f32_16x16x32_bf16 v[12:15], v[226:229], v[190:193], v[12:15]
	v_mfma_f32_16x16x32_bf16 v[4:7], v[218:221], v[210:213], v[4:7]
	v_mfma_f32_16x16x32_bf16 v[0:3], v[226:229], v[210:213], v[0:3]
	v_mfma_f32_16x16x32_bf16 v[52:55], v[222:225], v[178:181], v[52:55]
	v_mfma_f32_16x16x32_bf16 v[44:47], v[230:233], v[178:181], v[44:47]
	v_mfma_f32_16x16x32_bf16 v[36:39], v[222:225], v[186:189], v[36:39]
	v_mfma_f32_16x16x32_bf16 v[28:31], v[230:233], v[186:189], v[28:31]
	v_mfma_f32_16x16x32_bf16 v[20:23], v[222:225], v[206:209], v[20:23]
	v_mfma_f32_16x16x32_bf16 v[12:15], v[230:233], v[206:209], v[12:15]
	v_mfma_f32_16x16x32_bf16 v[4:7], v[222:225], v[214:217], v[4:7]
	v_mfma_f32_16x16x32_bf16 v[0:3], v[230:233], v[214:217], v[0:3]
	s_barrier
	s_cbranch_scc0 .LBB0_227
	v_lshl_add_u32 v140, s4, 8, v164
	s_cmp_gt_i32 s56, 23
	s_mov_b64 s[20:21], -1
	s_cbranch_scc1 .LBB0_262
	s_cmp_lt_i32 s56, 4
	s_cselect_b64 s[4:5], -1, 0
	s_and_b32 s6, s56, 0x7ffffffc
	s_cmp_eq_u32 s6, 16
	s_cselect_b64 s[6:7], -1, 0
	s_or_b64 s[20:21], s[4:5], s[6:7]
	s_and_b64 vcc, exec, s[20:21]
	v_mov_b32_e32 v149, v123
	v_mov_b32_e32 v148, v122
	v_mov_b32_e32 v163, v121
	v_mov_b32_e32 v162, v120
	v_mov_b32_e32 v147, v127
	v_mov_b32_e32 v146, v126
	v_mov_b32_e32 v151, v125
	v_mov_b32_e32 v150, v124
	s_cbranch_vccz .LBB0_231
	v_mul_f32_e32 v141, 0xbfb8aa3b, v124
	v_exp_f32_e32 v141, v141
	v_mul_f32_e32 v142, 0xbfb8aa3b, v120
	v_mul_f32_e32 v145, 0xbfb8aa3b, v126
	v_mul_f32_e32 v143, 0xbfb8aa3b, v125
	v_exp_f32_e32 v144, v142
	v_exp_f32_e32 v145, v145
	v_mul_f32_e32 v146, 0xbfb8aa3b, v122
	v_exp_f32_e32 v143, v143
	v_exp_f32_e32 v147, v146
	v_add_f32_e32 v141, 1.0, v141
	v_rcp_f32_e32 v142, v141
	v_add_f32_e32 v141, 1.0, v144
	v_add_f32_e32 v145, 1.0, v145
	v_rcp_f32_e32 v144, v141
	v_add_f32_e32 v141, 1.0, v143
	v_rcp_f32_e32 v146, v145
	v_add_f32_e32 v145, 1.0, v147
	v_mul_f32_e32 v147, 0xbfb8aa3b, v127
	v_rcp_f32_e32 v143, v141
	v_mul_f32_e32 v141, 0xbfb8aa3b, v121
	v_exp_f32_e32 v147, v147
	v_mul_f32_e32 v148, 0xbfb8aa3b, v123
	v_exp_f32_e32 v141, v141
	v_exp_f32_e32 v149, v148
	v_rcp_f32_e32 v148, v145
	v_add_f32_e32 v145, 1.0, v147
	v_add_f32_e32 v141, 1.0, v141
	v_rcp_f32_e32 v147, v145
	v_add_f32_e32 v145, 1.0, v149
	v_rcp_f32_e32 v149, v145
	v_rcp_f32_e32 v145, v141
	v_pk_mul_f32 v[146:147], v[126:127], v[146:147]
	v_pk_mul_f32 v[150:151], v[124:125], v[142:143]
	v_pk_mul_f32 v[148:149], v[122:123], v[148:149]
	v_pk_mul_f32 v[162:163], v[120:121], v[144:145]

.LBB0_560:
	s_ashr_i32 s17, s16, 31
	s_lshl_b64 s[6:7], s[16:17], 20
	v_cmp_lt_i64_e32 vcc, s[24:25], v[160:161]
	s_add_u32 s24, s56, s6
	s_addc_u32 s25, s57, s7
	s_and_b64 s[6:7], vcc, exec
	s_cselect_b32 s5, s25, s23
	s_cselect_b32 s6, s24, s22
	s_ashr_i32 s1, s0, 31
	s_lshl_b64 s[34:35], s[0:1], 20
	s_add_u32 s34, s58, s34
	s_addc_u32 s35, s59, s35
	s_and_b64 s[52:53], vcc, exec
	s_cselect_b32 s1, s35, s39
	s_cselect_b32 s7, s34, s38
	s_add_u32 s22, s22, 0x80080
	s_addc_u32 s23, s23, 0
	s_add_u32 s17, s38, 0x100
	v_mov_b32_e32 v0, 0
	s_addc_u32 s21, s39, 0
	s_mov_b32 s30, -2
	v_mov_b32_e32 v1, v0
	v_mov_b32_e32 v2, v0
	v_mov_b32_e32 v3, v0
	v_mov_b32_e32 v4, v0
	v_mov_b32_e32 v5, v0
	v_mov_b32_e32 v6, v0
	v_mov_b32_e32 v7, v0
	v_mov_b32_e32 v16, v0
	v_mov_b32_e32 v17, v0
	v_mov_b32_e32 v18, v0
	v_mov_b32_e32 v19, v0
	v_mov_b32_e32 v20, v0
	v_mov_b32_e32 v21, v0
	v_mov_b32_e32 v22, v0
	v_mov_b32_e32 v23, v0
	v_mov_b32_e32 v32, v0
	v_mov_b32_e32 v33, v0
	v_mov_b32_e32 v34, v0
	v_mov_b32_e32 v35, v0
	v_mov_b32_e32 v36, v0
	v_mov_b32_e32 v37, v0
	v_mov_b32_e32 v38, v0
	v_mov_b32_e32 v39, v0
	v_mov_b32_e32 v48, v0
	v_mov_b32_e32 v49, v0
	v_mov_b32_e32 v50, v0
	v_mov_b32_e32 v51, v0
	v_mov_b32_e32 v52, v0
	v_mov_b32_e32 v53, v0
	v_mov_b32_e32 v54, v0
	v_mov_b32_e32 v55, v0
	v_mov_b32_e32 v8, v0
	v_mov_b32_e32 v9, v0
	v_mov_b32_e32 v10, v0
	v_mov_b32_e32 v11, v0
	v_mov_b32_e32 v12, v0
	v_mov_b32_e32 v13, v0
	v_mov_b32_e32 v14, v0
	v_mov_b32_e32 v15, v0
	v_mov_b32_e32 v24, v0
	v_mov_b32_e32 v25, v0
	v_mov_b32_e32 v26, v0
	v_mov_b32_e32 v27, v0
	v_mov_b32_e32 v28, v0
	v_mov_b32_e32 v29, v0
	v_mov_b32_e32 v30, v0
	v_mov_b32_e32 v31, v0
	v_mov_b32_e32 v40, v0
	v_mov_b32_e32 v41, v0
	v_mov_b32_e32 v42, v0
	v_mov_b32_e32 v43, v0
	v_mov_b32_e32 v44, v0
	v_mov_b32_e32 v45, v0
	v_mov_b32_e32 v46, v0
	v_mov_b32_e32 v47, v0
	v_mov_b32_e32 v56, v0
	v_mov_b32_e32 v57, v0
	v_mov_b32_e32 v58, v0
	v_mov_b32_e32 v59, v0
	v_mov_b32_e32 v60, v0
	v_mov_b32_e32 v61, v0
	v_mov_b32_e32 v62, v0
	v_mov_b32_e32 v63, v0
	v_mov_b32_e32 v64, v0
	v_mov_b32_e32 v65, v0
	v_mov_b32_e32 v66, v0
	v_mov_b32_e32 v67, v0
	v_mov_b32_e32 v68, v0
	v_mov_b32_e32 v69, v0
	v_mov_b32_e32 v70, v0
	v_mov_b32_e32 v71, v0
	v_mov_b32_e32 v96, v0
	v_mov_b32_e32 v97, v0
	v_mov_b32_e32 v98, v0
	v_mov_b32_e32 v99, v0
	v_mov_b32_e32 v100, v0
	v_mov_b32_e32 v101, v0
	v_mov_b32_e32 v102, v0
	v_mov_b32_e32 v103, v0
	v_mov_b32_e32 v112, v0
	v_mov_b32_e32 v113, v0
	v_mov_b32_e32 v114, v0
	v_mov_b32_e32 v115, v0
	v_mov_b32_e32 v116, v0
	v_mov_b32_e32 v117, v0
	v_mov_b32_e32 v118, v0
	v_mov_b32_e32 v119, v0
	v_mov_b32_e32 v128, v0
	v_mov_b32_e32 v129, v0
	v_mov_b32_e32 v130, v0
	v_mov_b32_e32 v131, v0
	v_mov_b32_e32 v132, v0
	v_mov_b32_e32 v133, v0
	v_mov_b32_e32 v134, v0
	v_mov_b32_e32 v135, v0
	v_mov_b32_e32 v80, v0
	v_mov_b32_e32 v81, v0
	v_mov_b32_e32 v82, v0
	v_mov_b32_e32 v83, v0
	v_mov_b32_e32 v88, v0
	v_mov_b32_e32 v89, v0
	v_mov_b32_e32 v90, v0
	v_mov_b32_e32 v91, v0
	v_mov_b32_e32 v104, v0
	v_mov_b32_e32 v105, v0
	v_mov_b32_e32 v106, v0
	v_mov_b32_e32 v107, v0
	v_mov_b32_e32 v108, v0
	v_mov_b32_e32 v109, v0
	v_mov_b32_e32 v110, v0
	v_mov_b32_e32 v111, v0
	v_mov_b32_e32 v120, v0
	v_mov_b32_e32 v121, v0
	v_mov_b32_e32 v122, v0
	v_mov_b32_e32 v123, v0
	v_mov_b32_e32 v124, v0
	v_mov_b32_e32 v125, v0
	v_mov_b32_e32 v126, v0
	v_mov_b32_e32 v127, v0
	v_mov_b32_e32 v136, v0
	v_mov_b32_e32 v137, v0
	v_mov_b32_e32 v138, v0
	v_mov_b32_e32 v139, v0
	v_mov_b32_e32 v140, v0
	v_mov_b32_e32 v141, v0
	v_mov_b32_e32 v142, v0
	v_mov_b32_e32 v143, v0
	v_add_u32_e32 v246, 0x10000, v206
	v_add_u32_e32 v247, 0x14000, v206
	v_add_u32_e32 v248, 0x18000, v206
	v_add_u32_e32 v249, 0x1c000, v206
	s_add_u32 s38, s22, 0xfff80080
	s_addc_u32 s39, s23, -1
	s_add_i32 s84, 0, 0x10000
	s_cmp_eq_u32 s30, 28
	s_cselect_b32 s53, s5, s39
	s_cselect_b32 s52, s6, s38
	s_cselect_b32 s39, s1, s21
	s_cselect_b32 s38, s7, s17
	s_add_i32 m0, s61, 0xc000
.LBB0_561:
	ds_read_b128 v[72:75], v246
	ds_read_b128 v[76:79], v246 offset:1024
	ds_read_b128 v[84:87], v246 offset:2048
	ds_read_b128 v[92:95], v246 offset:3072
	ds_read_b128 v[144:147], v208
	ds_read_b128 v[148:151], v208 offset:1024
	ds_read_b128 v[188:191], v208 offset:2048
	ds_read_b128 v[210:213], v208 offset:3072
	ds_read_b128 v[214:217], v208 offset:4096
	ds_read_b128 v[218:221], v208 offset:5120
	ds_read_b128 v[222:225], v208 offset:6144
	ds_read_b128 v[226:229], v208 offset:7168
	global_load_lds_dwordx4 v184, s[22:23]
	s_add_i32 m0, s61, 0xe000
	s_nop 0
	global_load_lds_dwordx4 v186, s[22:23]
	s_waitcnt lgkmcnt(8)
	s_barrier
	s_waitcnt lgkmcnt(0)
	v_mfma_f32_16x16x32_bf16 v[140:143], v[72:75], v[144:147], v[140:143]
	v_mfma_f32_16x16x32_bf16 v[136:139], v[84:87], v[144:147], v[136:139]
	v_mfma_f32_16x16x32_bf16 v[124:127], v[72:75], v[188:191], v[124:127]
	v_mfma_f32_16x16x32_bf16 v[120:123], v[84:87], v[188:191], v[120:123]
	v_mfma_f32_16x16x32_bf16 v[108:111], v[72:75], v[214:217], v[108:111]
	v_mfma_f32_16x16x32_bf16 v[104:107], v[84:87], v[214:217], v[104:107]
	v_mfma_f32_16x16x32_bf16 v[88:91], v[72:75], v[222:225], v[88:91]
	v_mfma_f32_16x16x32_bf16 v[80:83], v[84:87], v[222:225], v[80:83]
	v_mfma_f32_16x16x32_bf16 v[140:143], v[76:79], v[148:151], v[140:143]
	v_mfma_f32_16x16x32_bf16 v[136:139], v[92:95], v[148:151], v[136:139]
	v_mfma_f32_16x16x32_bf16 v[124:127], v[76:79], v[210:213], v[124:127]
	v_mfma_f32_16x16x32_bf16 v[120:123], v[92:95], v[210:213], v[120:123]
	v_mfma_f32_16x16x32_bf16 v[108:111], v[76:79], v[218:221], v[108:111]
	v_mfma_f32_16x16x32_bf16 v[104:107], v[92:95], v[218:221], v[104:107]
	v_mfma_f32_16x16x32_bf16 v[88:91], v[76:79], v[226:229], v[88:91]
	v_mfma_f32_16x16x32_bf16 v[80:83], v[92:95], v[226:229], v[80:83]
	s_barrier
	s_add_i32 s86, 0, 0x14000
	s_add_i32 s84, s84, s60
	ds_read_b128 v[230:233], v247
	ds_read_b128 v[234:237], v247 offset:1024
	ds_read_b128 v[238:241], v247 offset:2048
	ds_read_b128 v[242:245], v247 offset:3072
	s_mov_b32 m0, s84
	s_nop 0
	global_load_lds_dwordx4 v152, s[38:39]
	s_add_i32 m0, s84, 0x2000
	s_nop 0
	global_load_lds_dwordx4 v162, s[38:39]
	s_barrier
	s_waitcnt lgkmcnt(0)
	v_mfma_f32_16x16x32_bf16 v[132:135], v[230:233], v[144:147], v[132:135]
	v_mfma_f32_16x16x32_bf16 v[128:131], v[238:241], v[144:147], v[128:131]
	v_mfma_f32_16x16x32_bf16 v[116:119], v[230:233], v[188:191], v[116:119]
	v_mfma_f32_16x16x32_bf16 v[112:115], v[238:241], v[188:191], v[112:115]
	v_mfma_f32_16x16x32_bf16 v[100:103], v[230:233], v[214:217], v[100:103]
	v_mfma_f32_16x16x32_bf16 v[96:99], v[238:241], v[214:217], v[96:99]
	v_mfma_f32_16x16x32_bf16 v[68:71], v[230:233], v[222:225], v[68:71]
	v_mfma_f32_16x16x32_bf16 v[64:67], v[238:241], v[222:225], v[64:67]
	v_mfma_f32_16x16x32_bf16 v[132:135], v[234:237], v[148:151], v[132:135]
	v_mfma_f32_16x16x32_bf16 v[128:131], v[242:245], v[148:151], v[128:131]
	v_mfma_f32_16x16x32_bf16 v[116:119], v[234:237], v[210:213], v[116:119]
	v_mfma_f32_16x16x32_bf16 v[112:115], v[242:245], v[210:213], v[112:115]
	v_mfma_f32_16x16x32_bf16 v[100:103], v[234:237], v[218:221], v[100:103]
	v_mfma_f32_16x16x32_bf16 v[96:99], v[242:245], v[218:221], v[96:99]
	v_mfma_f32_16x16x32_bf16 v[68:71], v[234:237], v[226:229], v[68:71]
	v_mfma_f32_16x16x32_bf16 v[64:67], v[242:245], v[226:229], v[64:67]
	s_barrier
	s_mov_b32 m0, s61
	s_add_u32 s98, s52, 0x80
	s_addc_u32 s99, s53, 0
	ds_read_b128 v[144:147], v208 offset:16384
	ds_read_b128 v[148:151], v208 offset:17408
	ds_read_b128 v[188:191], v208 offset:18432
	ds_read_b128 v[210:213], v208 offset:19456
	ds_read_b128 v[214:217], v208 offset:20480
	ds_read_b128 v[218:221], v208 offset:21504
	ds_read_b128 v[222:225], v208 offset:22528
	ds_read_b128 v[226:229], v208 offset:23552
	global_load_lds_dwordx4 v166, s[52:53]
	s_mov_b32 m0, s62
	s_nop 0
	global_load_lds_dwordx4 v164, s[52:53]
	s_barrier
	s_waitcnt lgkmcnt(0)
	v_mfma_f32_16x16x32_bf16 v[60:63], v[72:75], v[144:147], v[60:63]
	v_mfma_f32_16x16x32_bf16 v[56:59], v[84:87], v[144:147], v[56:59]
	v_mfma_f32_16x16x32_bf16 v[44:47], v[72:75], v[188:191], v[44:47]
	v_mfma_f32_16x16x32_bf16 v[40:43], v[84:87], v[188:191], v[40:43]
	v_mfma_f32_16x16x32_bf16 v[28:31], v[72:75], v[214:217], v[28:31]
	v_mfma_f32_16x16x32_bf16 v[24:27], v[84:87], v[214:217], v[24:27]
	v_mfma_f32_16x16x32_bf16 v[12:15], v[72:75], v[222:225], v[12:15]
	v_mfma_f32_16x16x32_bf16 v[8:11], v[84:87], v[222:225], v[8:11]
	v_mfma_f32_16x16x32_bf16 v[60:63], v[76:79], v[148:151], v[60:63]
	v_mfma_f32_16x16x32_bf16 v[56:59], v[92:95], v[148:151], v[56:59]
	v_mfma_f32_16x16x32_bf16 v[44:47], v[76:79], v[210:213], v[44:47]
	v_mfma_f32_16x16x32_bf16 v[40:43], v[92:95], v[210:213], v[40:43]
	v_mfma_f32_16x16x32_bf16 v[28:31], v[76:79], v[218:221], v[28:31]
	v_mfma_f32_16x16x32_bf16 v[24:27], v[92:95], v[218:221], v[24:27]
	v_mfma_f32_16x16x32_bf16 v[12:15], v[76:79], v[226:229], v[12:15]
	v_mfma_f32_16x16x32_bf16 v[8:11], v[92:95], v[226:229], v[8:11]
	s_barrier
	s_add_u32 s84, s38, 0x80000
	s_addc_u32 s85, s39, 0
	s_add_i32 s86, s86, s60
	s_mov_b32 m0, s86
	s_nop 0
	global_load_lds_dwordx4 v152, s[84:85]
	s_add_i32 m0, s86, 0x2000
	s_nop 0
	global_load_lds_dwordx4 v162, s[84:85]
	s_add_i32 s84, 0, 0x18000
	s_add_u32 s52, s52, 0x80000
	s_addc_u32 s53, s53, 0
	s_mov_b32 m0, s63
	s_waitcnt vmcnt(6)
	s_barrier
	v_mfma_f32_16x16x32_bf16 v[52:55], v[230:233], v[144:147], v[52:55]
	v_mfma_f32_16x16x32_bf16 v[48:51], v[238:241], v[144:147], v[48:51]
	v_mfma_f32_16x16x32_bf16 v[36:39], v[230:233], v[188:191], v[36:39]
	v_mfma_f32_16x16x32_bf16 v[32:35], v[238:241], v[188:191], v[32:35]
	v_mfma_f32_16x16x32_bf16 v[20:23], v[230:233], v[214:217], v[20:23]
	v_mfma_f32_16x16x32_bf16 v[16:19], v[238:241], v[214:217], v[16:19]
	v_mfma_f32_16x16x32_bf16 v[4:7], v[230:233], v[222:225], v[4:7]
	v_mfma_f32_16x16x32_bf16 v[0:3], v[238:241], v[222:225], v[0:3]
	v_mfma_f32_16x16x32_bf16 v[52:55], v[234:237], v[148:151], v[52:55]
	v_mfma_f32_16x16x32_bf16 v[48:51], v[242:245], v[148:151], v[48:51]
	v_mfma_f32_16x16x32_bf16 v[36:39], v[234:237], v[210:213], v[36:39]
	v_mfma_f32_16x16x32_bf16 v[32:35], v[242:245], v[210:213], v[32:35]
	v_mfma_f32_16x16x32_bf16 v[20:23], v[234:237], v[218:221], v[20:23]
	v_mfma_f32_16x16x32_bf16 v[16:19], v[242:245], v[218:221], v[16:19]
	v_mfma_f32_16x16x32_bf16 v[4:7], v[234:237], v[226:229], v[4:7]
	v_mfma_f32_16x16x32_bf16 v[0:3], v[242:245], v[226:229], v[0:3]
	s_barrier
	ds_read_b128 v[72:75], v248
	ds_read_b128 v[76:79], v248 offset:1024
	ds_read_b128 v[84:87], v248 offset:2048
	ds_read_b128 v[92:95], v248 offset:3072
	ds_read_b128 v[144:147], v208 offset:32768
	ds_read_b128 v[148:151], v208 offset:33792
	ds_read_b128 v[188:191], v208 offset:34816
	ds_read_b128 v[210:213], v208 offset:35840
	ds_read_b128 v[214:217], v208 offset:36864
	ds_read_b128 v[218:221], v208 offset:37888
	ds_read_b128 v[222:225], v208 offset:38912
	ds_read_b128 v[226:229], v208 offset:39936
	global_load_lds_dwordx4 v166, s[52:53]
	s_mov_b32 m0, s68
	s_nop 0
	global_load_lds_dwordx4 v164, s[52:53]
	s_waitcnt lgkmcnt(8)
	s_barrier
	s_waitcnt lgkmcnt(0)
	v_mfma_f32_16x16x32_bf16 v[140:143], v[72:75], v[144:147], v[140:143]
	v_mfma_f32_16x16x32_bf16 v[136:139], v[84:87], v[144:147], v[136:139]
	v_mfma_f32_16x16x32_bf16 v[124:127], v[72:75], v[188:191], v[124:127]
	v_mfma_f32_16x16x32_bf16 v[120:123], v[84:87], v[188:191], v[120:123]
	v_mfma_f32_16x16x32_bf16 v[108:111], v[72:75], v[214:217], v[108:111]
	v_mfma_f32_16x16x32_bf16 v[104:107], v[84:87], v[214:217], v[104:107]
	v_mfma_f32_16x16x32_bf16 v[88:91], v[72:75], v[222:225], v[88:91]
	v_mfma_f32_16x16x32_bf16 v[80:83], v[84:87], v[222:225], v[80:83]
	v_mfma_f32_16x16x32_bf16 v[140:143], v[76:79], v[148:151], v[140:143]
	v_mfma_f32_16x16x32_bf16 v[136:139], v[92:95], v[148:151], v[136:139]
	v_mfma_f32_16x16x32_bf16 v[124:127], v[76:79], v[210:213], v[124:127]
	v_mfma_f32_16x16x32_bf16 v[120:123], v[92:95], v[210:213], v[120:123]
	v_mfma_f32_16x16x32_bf16 v[108:111], v[76:79], v[218:221], v[108:111]
	v_mfma_f32_16x16x32_bf16 v[104:107], v[92:95], v[218:221], v[104:107]
	v_mfma_f32_16x16x32_bf16 v[88:91], v[76:79], v[226:229], v[88:91]
	v_mfma_f32_16x16x32_bf16 v[80:83], v[92:95], v[226:229], v[80:83]
	s_barrier
	s_add_i32 s52, 0, 0x1c000
	s_add_i32 s53, s84, s60
	s_add_u32 s100, s38, 0x80
	s_addc_u32 s101, s39, 0
	s_mov_b32 m0, s53
	ds_read_b128 v[230:233], v249
	ds_read_b128 v[234:237], v249 offset:1024
	ds_read_b128 v[238:241], v249 offset:2048
	ds_read_b128 v[242:245], v249 offset:3072
	global_load_lds_dwordx4 v152, s[100:101]
	s_add_i32 m0, s53, 0x2000
	s_nop 0
	global_load_lds_dwordx4 v162, s[100:101]
	s_barrier
	s_waitcnt lgkmcnt(0)
	v_mfma_f32_16x16x32_bf16 v[132:135], v[230:233], v[144:147], v[132:135]
	v_mfma_f32_16x16x32_bf16 v[128:131], v[238:241], v[144:147], v[128:131]
	v_mfma_f32_16x16x32_bf16 v[116:119], v[230:233], v[188:191], v[116:119]
	v_mfma_f32_16x16x32_bf16 v[112:115], v[238:241], v[188:191], v[112:115]
	v_mfma_f32_16x16x32_bf16 v[100:103], v[230:233], v[214:217], v[100:103]
	v_mfma_f32_16x16x32_bf16 v[96:99], v[238:241], v[214:217], v[96:99]
	v_mfma_f32_16x16x32_bf16 v[68:71], v[230:233], v[222:225], v[68:71]
	v_mfma_f32_16x16x32_bf16 v[64:67], v[238:241], v[222:225], v[64:67]
	v_mfma_f32_16x16x32_bf16 v[132:135], v[234:237], v[148:151], v[132:135]
	v_mfma_f32_16x16x32_bf16 v[128:131], v[242:245], v[148:151], v[128:131]
	v_mfma_f32_16x16x32_bf16 v[116:119], v[234:237], v[210:213], v[116:119]
	v_mfma_f32_16x16x32_bf16 v[112:115], v[242:245], v[210:213], v[112:115]
	v_mfma_f32_16x16x32_bf16 v[100:103], v[234:237], v[218:221], v[100:103]
	v_mfma_f32_16x16x32_bf16 v[96:99], v[242:245], v[218:221], v[96:99]
	v_mfma_f32_16x16x32_bf16 v[68:71], v[234:237], v[226:229], v[68:71]
	v_mfma_f32_16x16x32_bf16 v[64:67], v[242:245], v[226:229], v[64:67]
	s_barrier
	s_mov_b32 m0, s81
	ds_read_b128 v[144:147], v208 offset:49152
	ds_read_b128 v[148:151], v208 offset:50176
	ds_read_b128 v[188:191], v208 offset:51200
	ds_read_b128 v[210:213], v208 offset:52224
	ds_read_b128 v[214:217], v208 offset:53248
	ds_read_b128 v[218:221], v208 offset:54272
	ds_read_b128 v[222:225], v208 offset:55296
	ds_read_b128 v[226:229], v208 offset:56320
	global_load_lds_dwordx4 v166, s[98:99]
	s_mov_b32 m0, s82
	s_nop 0
	global_load_lds_dwordx4 v164, s[98:99]
	s_barrier
	s_waitcnt lgkmcnt(0)
	v_mfma_f32_16x16x32_bf16 v[60:63], v[72:75], v[144:147], v[60:63]
	v_mfma_f32_16x16x32_bf16 v[56:59], v[84:87], v[144:147], v[56:59]
	v_mfma_f32_16x16x32_bf16 v[44:47], v[72:75], v[188:191], v[44:47]
	v_mfma_f32_16x16x32_bf16 v[40:43], v[84:87], v[188:191], v[40:43]
	v_mfma_f32_16x16x32_bf16 v[28:31], v[72:75], v[214:217], v[28:31]
	v_mfma_f32_16x16x32_bf16 v[24:27], v[84:87], v[214:217], v[24:27]
	v_mfma_f32_16x16x32_bf16 v[12:15], v[72:75], v[222:225], v[12:15]
	v_mfma_f32_16x16x32_bf16 v[8:11], v[84:87], v[222:225], v[8:11]
	v_mfma_f32_16x16x32_bf16 v[60:63], v[76:79], v[148:151], v[60:63]
	v_mfma_f32_16x16x32_bf16 v[56:59], v[92:95], v[148:151], v[56:59]
	v_mfma_f32_16x16x32_bf16 v[44:47], v[76:79], v[210:213], v[44:47]
	v_mfma_f32_16x16x32_bf16 v[40:43], v[92:95], v[210:213], v[40:43]
	v_mfma_f32_16x16x32_bf16 v[28:31], v[76:79], v[218:221], v[28:31]
	v_mfma_f32_16x16x32_bf16 v[24:27], v[92:95], v[218:221], v[24:27]
	v_mfma_f32_16x16x32_bf16 v[12:15], v[76:79], v[226:229], v[12:15]
	v_mfma_f32_16x16x32_bf16 v[8:11], v[92:95], v[226:229], v[8:11]
	s_barrier
	s_add_u32 s38, s38, 0x80080
	s_addc_u32 s39, s39, 0
	s_add_i32 s52, s52, s60
	s_mov_b32 m0, s52
	s_nop 0
	global_load_lds_dwordx4 v152, s[38:39]
	s_add_i32 m0, s52, 0x2000
	s_nop 0
	global_load_lds_dwordx4 v162, s[38:39]
	s_add_i32 s30, s30, 2
	s_add_u32 s22, s22, 0x100
	s_addc_u32 s23, s23, 0
	s_add_u32 s17, s17, 0x100
	s_addc_u32 s21, s21, 0
	s_add_u32 s38, s22, 0xfff80080
	s_addc_u32 s39, s23, -1
	s_add_i32 s84, 0, 0x10000
	s_cmp_eq_u32 s30, 28
	s_cselect_b32 s53, s5, s39
	s_cselect_b32 s52, s6, s38
	s_cselect_b32 s39, s1, s21
	s_cselect_b32 s38, s7, s17
	s_add_i32 m0, s61, 0xc000
	s_cmp_gt_u32 s30, 29
	s_waitcnt vmcnt(6)
	s_barrier
	v_mfma_f32_16x16x32_bf16 v[52:55], v[230:233], v[144:147], v[52:55]
	v_mfma_f32_16x16x32_bf16 v[48:51], v[238:241], v[144:147], v[48:51]
	v_mfma_f32_16x16x32_bf16 v[36:39], v[230:233], v[188:191], v[36:39]
	v_mfma_f32_16x16x32_bf16 v[32:35], v[238:241], v[188:191], v[32:35]
	v_mfma_f32_16x16x32_bf16 v[20:23], v[230:233], v[214:217], v[20:23]
	v_mfma_f32_16x16x32_bf16 v[16:19], v[238:241], v[214:217], v[16:19]
	v_mfma_f32_16x16x32_bf16 v[4:7], v[230:233], v[222:225], v[4:7]
	v_mfma_f32_16x16x32_bf16 v[0:3], v[238:241], v[222:225], v[0:3]
	v_mfma_f32_16x16x32_bf16 v[52:55], v[234:237], v[148:151], v[52:55]
	v_mfma_f32_16x16x32_bf16 v[48:51], v[242:245], v[148:151], v[48:51]
	v_mfma_f32_16x16x32_bf16 v[36:39], v[234:237], v[210:213], v[36:39]
	v_mfma_f32_16x16x32_bf16 v[32:35], v[242:245], v[210:213], v[32:35]
	v_mfma_f32_16x16x32_bf16 v[20:23], v[234:237], v[218:221], v[20:23]
	v_mfma_f32_16x16x32_bf16 v[16:19], v[242:245], v[218:221], v[16:19]
	v_mfma_f32_16x16x32_bf16 v[4:7], v[234:237], v[226:229], v[4:7]
	v_mfma_f32_16x16x32_bf16 v[0:3], v[242:245], v[226:229], v[0:3]
	s_barrier
	s_cbranch_scc0 .LBB0_561
	v_lshl_or_b32 v188, s4, 8, v207
	v_ashrrev_i32_e32 v189, 31, v188
	s_cmp_lt_i32 s20, 16
	s_cselect_b32 s6, s44, s46
	s_cselect_b32 s7, s45, s47
	s_cselect_b32 s1, 0, 16
	s_sub_i32 s4, s20, s1
	s_mov_b32 s5, 0
	s_lshl_b64 s[4:5], s[4:5], 21
	s_add_u32 s38, s6, s4
	s_addc_u32 s39, s7, s5
	s_cmp_lt_i32 s20, 32
	s_cselect_b32 s1, 0x3000, s73
	s_cmp_lt_i32 s20, 16
	s_cselect_b32 s1, 0, s1
	s_lshl_b32 s1, s1, 2
	s_add_u32 s6, s79, s1
	s_addc_u32 s7, s80, 0
	s_mov_b32 s4, s20
	s_mov_b32 s5, 0
	s_lshl_b64 s[4:5], s[4:5], 20
	s_add_u32 s52, s69, s4
	s_addc_u32 s53, s78, s5
	v_lshl_add_u64 v[190:191], v[188:189], 2, s[6:7]
	s_mov_b64 s[4:5], 0x28504000
	v_lshl_add_u64 v[190:191], v[190:191], 0, s[4:5]
	global_load_dwordx4 v[92:95], v[190:191], off
	global_load_dwordx4 v[84:87], v[190:191], off offset:16
	global_load_dwordx4 v[76:79], v[190:191], off offset:512
	global_load_dwordx4 v[72:75], v[190:191], off offset:528
	v_lshl_add_u64 v[144:145], v[188:189], 1, s[52:53]
	s_and_b64 vcc, exec, s[64:65]
	s_cbranch_vccz .Lwo_epi_f32
	v_lshl_add_u64 v[148:149], v[168:169], 1, v[144:145]
	global_load_dwordx4 v[210:213], v[148:149], off
	global_load_dwordx4 v[214:217], v[148:149], off offset:256
	v_lshl_add_u64 v[148:149], v[170:171], 1, v[144:145]
	global_load_dwordx4 v[218:221], v[148:149], off
	global_load_dwordx4 v[222:225], v[148:149], off offset:256
	v_lshl_add_u64 v[148:149], v[172:173], 1, v[144:145]
	global_load_dwordx4 v[226:229], v[148:149], off
	global_load_dwordx4 v[230:233], v[148:149], off offset:256
	v_lshl_add_u64 v[148:149], v[174:175], 1, v[144:145]
	global_load_dwordx4 v[234:237], v[148:149], off
	global_load_dwordx4 v[238:241], v[148:149], off offset:256
	v_lshl_add_u64 v[148:149], v[176:177], 1, v[144:145]
	global_load_dwordx4 v[242:245], v[148:149], off
	s_waitcnt vmcnt(8)
	v_lshlrev_b32_e32 v188, 16, v210
	v_and_b32_e32 v189, 0xffff0000, v210
	v_lshlrev_b32_e32 v190, 16, v211
	v_and_b32_e32 v191, 0xffff0000, v211
	v_lshlrev_b32_e32 v246, 16, v212
	v_and_b32_e32 v247, 0xffff0000, v212
	v_lshlrev_b32_e32 v248, 16, v213
	v_and_b32_e32 v249, 0xffff0000, v213
	global_load_dwordx4 v[210:213], v[148:149], off offset:256
	v_lshl_add_u64 v[150:151], v[168:169], 1, v[144:145]
	v_pk_fma_f32 v[140:141], v[140:141], v[92:93], v[188:189]
	v_pk_fma_f32 v[142:143], v[142:143], v[94:95], v[190:191]
	v_pk_fma_f32 v[136:137], v[136:137], v[84:85], v[246:247]
	v_pk_fma_f32 v[138:139], v[138:139], v[86:87], v[248:249]
	v_cvt_pk_bf16_f32 v140, v140, v141
	v_cvt_pk_bf16_f32 v141, v142, v143
	v_cvt_pk_bf16_f32 v142, v136, v137
	v_cvt_pk_bf16_f32 v143, v138, v139
	global_store_dwordx4 v[150:151], v[140:143], off
	s_waitcnt vmcnt(9)
	v_lshlrev_b32_e32 v188, 16, v214
	v_and_b32_e32 v189, 0xffff0000, v214
	v_lshlrev_b32_e32 v190, 16, v215
	v_and_b32_e32 v191, 0xffff0000, v215
	v_lshlrev_b32_e32 v246, 16, v216
	v_and_b32_e32 v247, 0xffff0000, v216
	v_lshlrev_b32_e32 v248, 16, v217
	v_and_b32_e32 v249, 0xffff0000, v217
	v_lshl_add_u64 v[148:149], v[178:179], 1, v[144:145]
	global_load_dwordx4 v[214:217], v[148:149], off
	v_pk_fma_f32 v[132:133], v[132:133], v[76:77], v[188:189]
	v_pk_fma_f32 v[134:135], v[134:135], v[78:79], v[190:191]
	v_pk_fma_f32 v[128:129], v[128:129], v[72:73], v[246:247]
	v_pk_fma_f32 v[130:131], v[130:131], v[74:75], v[248:249]
	v_cvt_pk_bf16_f32 v132, v132, v133
	v_cvt_pk_bf16_f32 v133, v134, v135
	v_cvt_pk_bf16_f32 v134, v128, v129
	v_cvt_pk_bf16_f32 v135, v130, v131
	global_store_dwordx4 v[150:151], v[132:135], off offset:256
	s_waitcnt vmcnt(10)
	v_lshlrev_b32_e32 v188, 16, v218
	v_and_b32_e32 v189, 0xffff0000, v218
	v_lshlrev_b32_e32 v190, 16, v219
	v_and_b32_e32 v191, 0xffff0000, v219
	v_lshlrev_b32_e32 v246, 16, v220
	v_and_b32_e32 v247, 0xffff0000, v220
	v_lshlrev_b32_e32 v248, 16, v221
	v_and_b32_e32 v249, 0xffff0000, v221
	global_load_dwordx4 v[218:221], v[148:149], off offset:256
	v_lshl_add_u64 v[192:193], v[170:171], 1, v[144:145]
	v_pk_fma_f32 v[124:125], v[124:125], v[92:93], v[188:189]
	v_pk_fma_f32 v[126:127], v[126:127], v[94:95], v[190:191]
	v_pk_fma_f32 v[120:121], v[120:121], v[84:85], v[246:247]
	v_pk_fma_f32 v[122:123], v[122:123], v[86:87], v[248:249]
	v_cvt_pk_bf16_f32 v124, v124, v125
	v_cvt_pk_bf16_f32 v125, v126, v127
	v_cvt_pk_bf16_f32 v126, v120, v121
	v_cvt_pk_bf16_f32 v127, v122, v123
	global_store_dwordx4 v[192:193], v[124:127], off
	s_waitcnt vmcnt(11)
	v_lshlrev_b32_e32 v188, 16, v222
	v_and_b32_e32 v189, 0xffff0000, v222
	v_lshlrev_b32_e32 v190, 16, v223
	v_and_b32_e32 v191, 0xffff0000, v223
	v_lshlrev_b32_e32 v246, 16, v224
	v_and_b32_e32 v247, 0xffff0000, v224
	v_lshlrev_b32_e32 v248, 16, v225
	v_and_b32_e32 v249, 0xffff0000, v225
	v_lshl_add_u64 v[148:149], v[180:181], 1, v[144:145]
	global_load_dwordx4 v[222:225], v[148:149], off
	v_pk_fma_f32 v[116:117], v[116:117], v[76:77], v[188:189]
	v_pk_fma_f32 v[118:119], v[118:119], v[78:79], v[190:191]
	v_pk_fma_f32 v[112:113], v[112:113], v[72:73], v[246:247]
	v_pk_fma_f32 v[114:115], v[114:115], v[74:75], v[248:249]
	v_cvt_pk_bf16_f32 v116, v116, v117
	v_cvt_pk_bf16_f32 v117, v118, v119
	v_cvt_pk_bf16_f32 v118, v112, v113
	v_cvt_pk_bf16_f32 v119, v114, v115
	global_store_dwordx4 v[192:193], v[116:119], off offset:256
	s_waitcnt vmcnt(12)
	v_lshlrev_b32_e32 v188, 16, v226
	v_and_b32_e32 v189, 0xffff0000, v226
	v_lshlrev_b32_e32 v190, 16, v227
	v_and_b32_e32 v191, 0xffff0000, v227
	v_lshlrev_b32_e32 v246, 16, v228
	v_and_b32_e32 v247, 0xffff0000, v228
	v_lshlrev_b32_e32 v248, 16, v229
	v_and_b32_e32 v249, 0xffff0000, v229
	global_load_dwordx4 v[226:229], v[148:149], off offset:256
	v_lshl_add_u64 v[150:151], v[172:173], 1, v[144:145]
	v_pk_fma_f32 v[108:109], v[108:109], v[92:93], v[188:189]
	v_pk_fma_f32 v[110:111], v[110:111], v[94:95], v[190:191]
	v_pk_fma_f32 v[104:105], v[104:105], v[84:85], v[246:247]
	v_pk_fma_f32 v[106:107], v[106:107], v[86:87], v[248:249]
	v_cvt_pk_bf16_f32 v108, v108, v109
	v_cvt_pk_bf16_f32 v109, v110, v111
	v_cvt_pk_bf16_f32 v110, v104, v105
	v_cvt_pk_bf16_f32 v111, v106, v107
	global_store_dwordx4 v[150:151], v[108:111], off
	s_waitcnt vmcnt(13)
	v_lshlrev_b32_e32 v188, 16, v230
	v_and_b32_e32 v189, 0xffff0000, v230
	v_lshlrev_b32_e32 v190, 16, v231
	v_and_b32_e32 v191, 0xffff0000, v231
	v_lshlrev_b32_e32 v246, 16, v232
	v_and_b32_e32 v247, 0xffff0000, v232
	v_lshlrev_b32_e32 v248, 16, v233
	v_and_b32_e32 v249, 0xffff0000, v233
	v_lshl_add_u64 v[148:149], v[182:183], 1, v[144:145]
	global_load_dwordx4 v[230:233], v[148:149], off
	v_pk_fma_f32 v[100:101], v[100:101], v[76:77], v[188:189]
	v_pk_fma_f32 v[102:103], v[102:103], v[78:79], v[190:191]
	v_pk_fma_f32 v[96:97], v[96:97], v[72:73], v[246:247]
	v_pk_fma_f32 v[98:99], v[98:99], v[74:75], v[248:249]
	v_cvt_pk_bf16_f32 v100, v100, v101
	v_cvt_pk_bf16_f32 v101, v102, v103
	v_cvt_pk_bf16_f32 v102, v96, v97
	v_cvt_pk_bf16_f32 v103, v98, v99
	global_store_dwordx4 v[150:151], v[100:103], off offset:256
	s_waitcnt vmcnt(14)
	v_lshlrev_b32_e32 v188, 16, v234
	v_and_b32_e32 v189, 0xffff0000, v234
	v_lshlrev_b32_e32 v190, 16, v235
	v_and_b32_e32 v191, 0xffff0000, v235
	v_lshlrev_b32_e32 v246, 16, v236
	v_and_b32_e32 v247, 0xffff0000, v236
	v_lshlrev_b32_e32 v248, 16, v237
	v_and_b32_e32 v249, 0xffff0000, v237
	global_load_dwordx4 v[234:237], v[148:149], off offset:256
	v_lshl_add_u64 v[192:193], v[174:175], 1, v[144:145]
	v_pk_fma_f32 v[88:89], v[88:89], v[92:93], v[188:189]
	v_pk_fma_f32 v[90:91], v[90:91], v[94:95], v[190:191]
	v_pk_fma_f32 v[80:81], v[80:81], v[84:85], v[246:247]
	v_pk_fma_f32 v[82:83], v[82:83], v[86:87], v[248:249]
	v_cvt_pk_bf16_f32 v88, v88, v89
	v_cvt_pk_bf16_f32 v89, v90, v91
	v_cvt_pk_bf16_f32 v90, v80, v81
	v_cvt_pk_bf16_f32 v91, v82, v83
	global_store_dwordx4 v[192:193], v[88:91], off
	s_waitcnt vmcnt(15)
	v_lshlrev_b32_e32 v188, 16, v238
	v_and_b32_e32 v189, 0xffff0000, v238
	v_lshlrev_b32_e32 v190, 16, v239
	v_and_b32_e32 v191, 0xffff0000, v239
	v_lshlrev_b32_e32 v246, 16, v240
	v_and_b32_e32 v247, 0xffff0000, v240
	v_lshlrev_b32_e32 v248, 16, v241
	v_and_b32_e32 v249, 0xffff0000, v241
	v_pk_fma_f32 v[68:69], v[68:69], v[76:77], v[188:189]
	v_pk_fma_f32 v[70:71], v[70:71], v[78:79], v[190:191]
	v_pk_fma_f32 v[64:65], v[64:65], v[72:73], v[246:247]
	v_pk_fma_f32 v[66:67], v[66:67], v[74:75], v[248:249]
	v_cvt_pk_bf16_f32 v68, v68, v69
	v_cvt_pk_bf16_f32 v69, v70, v71
	v_cvt_pk_bf16_f32 v70, v64, v65
	v_cvt_pk_bf16_f32 v71, v66, v67
	global_store_dwordx4 v[192:193], v[68:71], off offset:256
	s_waitcnt vmcnt(15)
	v_lshlrev_b32_e32 v188, 16, v242
	v_and_b32_e32 v189, 0xffff0000, v242
	v_lshlrev_b32_e32 v190, 16, v243
	v_and_b32_e32 v191, 0xffff0000, v243
	v_lshlrev_b32_e32 v246, 16, v244
	v_and_b32_e32 v247, 0xffff0000, v244
	v_lshlrev_b32_e32 v248, 16, v245
	v_and_b32_e32 v249, 0xffff0000, v245
	v_lshl_add_u64 v[150:151], v[176:177], 1, v[144:145]
	v_pk_fma_f32 v[60:61], v[60:61], v[92:93], v[188:189]
	v_pk_fma_f32 v[62:63], v[62:63], v[94:95], v[190:191]
	v_pk_fma_f32 v[56:57], v[56:57], v[84:85], v[246:247]
	v_pk_fma_f32 v[58:59], v[58:59], v[86:87], v[248:249]
	v_cvt_pk_bf16_f32 v60, v60, v61
	v_cvt_pk_bf16_f32 v61, v62, v63
	v_cvt_pk_bf16_f32 v62, v56, v57
	v_cvt_pk_bf16_f32 v63, v58, v59
	global_store_dwordx4 v[150:151], v[60:63], off
	s_waitcnt vmcnt(15)
	v_lshlrev_b32_e32 v188, 16, v210
	v_and_b32_e32 v189, 0xffff0000, v210
	v_lshlrev_b32_e32 v190, 16, v211
	v_and_b32_e32 v191, 0xffff0000, v211
	v_lshlrev_b32_e32 v246, 16, v212
	v_and_b32_e32 v247, 0xffff0000, v212
	v_lshlrev_b32_e32 v248, 16, v213
	v_and_b32_e32 v249, 0xffff0000, v213
	v_pk_fma_f32 v[52:53], v[52:53], v[76:77], v[188:189]
	v_pk_fma_f32 v[54:55], v[54:55], v[78:79], v[190:191]
	v_pk_fma_f32 v[48:49], v[48:49], v[72:73], v[246:247]
	v_pk_fma_f32 v[50:51], v[50:51], v[74:75], v[248:249]
	v_cvt_pk_bf16_f32 v52, v52, v53
	v_cvt_pk_bf16_f32 v53, v54, v55
	v_cvt_pk_bf16_f32 v54, v48, v49
	v_cvt_pk_bf16_f32 v55, v50, v51
	global_store_dwordx4 v[150:151], v[52:55], off offset:256
	s_waitcnt vmcnt(14)
	v_lshlrev_b32_e32 v188, 16, v214
	v_and_b32_e32 v189, 0xffff0000, v214
	v_lshlrev_b32_e32 v190, 16, v215
	v_and_b32_e32 v191, 0xffff0000, v215
	v_lshlrev_b32_e32 v246, 16, v216
	v_and_b32_e32 v247, 0xffff0000, v216
	v_lshlrev_b32_e32 v248, 16, v217
	v_and_b32_e32 v249, 0xffff0000, v217
	v_lshl_add_u64 v[192:193], v[178:179], 1, v[144:145]
	v_pk_fma_f32 v[44:45], v[44:45], v[92:93], v[188:189]
	v_pk_fma_f32 v[46:47], v[46:47], v[94:95], v[190:191]
	v_pk_fma_f32 v[40:41], v[40:41], v[84:85], v[246:247]
	v_pk_fma_f32 v[42:43], v[42:43], v[86:87], v[248:249]
	v_cvt_pk_bf16_f32 v44, v44, v45
	v_cvt_pk_bf16_f32 v45, v46, v47
	v_cvt_pk_bf16_f32 v46, v40, v41
	v_cvt_pk_bf16_f32 v47, v42, v43
	global_store_dwordx4 v[192:193], v[44:47], off
	s_waitcnt vmcnt(13)
	v_lshlrev_b32_e32 v188, 16, v218
	v_and_b32_e32 v189, 0xffff0000, v218
	v_lshlrev_b32_e32 v190, 16, v219
	v_and_b32_e32 v191, 0xffff0000, v219
	v_lshlrev_b32_e32 v246, 16, v220
	v_and_b32_e32 v247, 0xffff0000, v220
	v_lshlrev_b32_e32 v248, 16, v221
	v_and_b32_e32 v249, 0xffff0000, v221
	v_pk_fma_f32 v[36:37], v[36:37], v[76:77], v[188:189]
	v_pk_fma_f32 v[38:39], v[38:39], v[78:79], v[190:191]
	v_pk_fma_f32 v[32:33], v[32:33], v[72:73], v[246:247]
	v_pk_fma_f32 v[34:35], v[34:35], v[74:75], v[248:249]
	v_cvt_pk_bf16_f32 v36, v36, v37
	v_cvt_pk_bf16_f32 v37, v38, v39
	v_cvt_pk_bf16_f32 v38, v32, v33
	v_cvt_pk_bf16_f32 v39, v34, v35
	global_store_dwordx4 v[192:193], v[36:39], off offset:256
	s_waitcnt vmcnt(12)
	v_lshlrev_b32_e32 v188, 16, v222
	v_and_b32_e32 v189, 0xffff0000, v222
	v_lshlrev_b32_e32 v190, 16, v223
	v_and_b32_e32 v191, 0xffff0000, v223
	v_lshlrev_b32_e32 v246, 16, v224
	v_and_b32_e32 v247, 0xffff0000, v224
	v_lshlrev_b32_e32 v248, 16, v225
	v_and_b32_e32 v249, 0xffff0000, v225
	v_lshl_add_u64 v[150:151], v[180:181], 1, v[144:145]
	v_pk_fma_f32 v[28:29], v[28:29], v[92:93], v[188:189]
	v_pk_fma_f32 v[30:31], v[30:31], v[94:95], v[190:191]
	v_pk_fma_f32 v[24:25], v[24:25], v[84:85], v[246:247]
	v_pk_fma_f32 v[26:27], v[26:27], v[86:87], v[248:249]
	v_cvt_pk_bf16_f32 v28, v28, v29
	v_cvt_pk_bf16_f32 v29, v30, v31
	v_cvt_pk_bf16_f32 v30, v24, v25
	v_cvt_pk_bf16_f32 v31, v26, v27
	global_store_dwordx4 v[150:151], v[28:31], off
	s_waitcnt vmcnt(11)
	v_lshlrev_b32_e32 v188, 16, v226
	v_and_b32_e32 v189, 0xffff0000, v226
	v_lshlrev_b32_e32 v190, 16, v227
	v_and_b32_e32 v191, 0xffff0000, v227
	v_lshlrev_b32_e32 v246, 16, v228
	v_and_b32_e32 v247, 0xffff0000, v228
	v_lshlrev_b32_e32 v248, 16, v229
	v_and_b32_e32 v249, 0xffff0000, v229
	v_pk_fma_f32 v[20:21], v[20:21], v[76:77], v[188:189]
	v_pk_fma_f32 v[22:23], v[22:23], v[78:79], v[190:191]
	v_pk_fma_f32 v[16:17], v[16:17], v[72:73], v[246:247]
	v_pk_fma_f32 v[18:19], v[18:19], v[74:75], v[248:249]
	v_cvt_pk_bf16_f32 v20, v20, v21
	v_cvt_pk_bf16_f32 v21, v22, v23
	v_cvt_pk_bf16_f32 v22, v16, v17
	v_cvt_pk_bf16_f32 v23, v18, v19
	global_store_dwordx4 v[150:151], v[20:23], off offset:256
	s_waitcnt vmcnt(10)
	v_lshlrev_b32_e32 v188, 16, v230
	v_and_b32_e32 v189, 0xffff0000, v230
	v_lshlrev_b32_e32 v190, 16, v231
	v_and_b32_e32 v191, 0xffff0000, v231
	v_lshlrev_b32_e32 v246, 16, v232
	v_and_b32_e32 v247, 0xffff0000, v232
	v_lshlrev_b32_e32 v248, 16, v233
	v_and_b32_e32 v249, 0xffff0000, v233
	v_lshl_add_u64 v[192:193], v[182:183], 1, v[144:145]
	v_pk_fma_f32 v[12:13], v[12:13], v[92:93], v[188:189]
	v_pk_fma_f32 v[14:15], v[14:15], v[94:95], v[190:191]
	v_pk_fma_f32 v[8:9], v[8:9], v[84:85], v[246:247]
	v_pk_fma_f32 v[10:11], v[10:11], v[86:87], v[248:249]
	v_cvt_pk_bf16_f32 v12, v12, v13
	v_cvt_pk_bf16_f32 v13, v14, v15
	v_cvt_pk_bf16_f32 v14, v8, v9
	v_cvt_pk_bf16_f32 v15, v10, v11
	global_store_dwordx4 v[192:193], v[12:15], off
	s_waitcnt vmcnt(9)
	v_lshlrev_b32_e32 v188, 16, v234
	v_and_b32_e32 v189, 0xffff0000, v234
	v_lshlrev_b32_e32 v190, 16, v235
	v_and_b32_e32 v191, 0xffff0000, v235
	v_lshlrev_b32_e32 v246, 16, v236
	v_and_b32_e32 v247, 0xffff0000, v236
	v_lshlrev_b32_e32 v248, 16, v237
	v_and_b32_e32 v249, 0xffff0000, v237
	v_pk_fma_f32 v[4:5], v[4:5], v[76:77], v[188:189]
	v_pk_fma_f32 v[6:7], v[6:7], v[78:79], v[190:191]
	v_pk_fma_f32 v[0:1], v[0:1], v[72:73], v[246:247]
	v_pk_fma_f32 v[2:3], v[2:3], v[74:75], v[248:249]
	v_cvt_pk_bf16_f32 v4, v4, v5
	v_cvt_pk_bf16_f32 v5, v6, v7
	v_cvt_pk_bf16_f32 v6, v0, v1
	v_cvt_pk_bf16_f32 v7, v2, v3
	global_store_dwordx4 v[192:193], v[4:7], off offset:256
	s_branch .Lwo_epi_done

.LBB0_772:
	s_ashr_i32 s35, s34, 31
	v_cmp_lt_i64_e32 vcc, s[42:43], v[156:157]
	s_lshl_b64 s[42:43], s[34:35], 20
	s_add_u32 s42, s15, s42
	s_addc_u32 s43, s30, s43
	s_and_b64 s[44:45], vcc, exec
	s_cselect_b32 s35, s43, s21
	s_cselect_b32 s56, s42, s20
	s_ashr_i32 s25, s24, 31
	s_lshl_b64 s[44:45], s[24:25], 20
	s_add_u32 s44, s48, s44
	s_addc_u32 s45, s49, s45
	s_and_b64 s[46:47], vcc, exec
	s_cselect_b32 s25, s45, s23
	s_cselect_b32 s57, s44, s22
	s_add_u32 s20, s20, 0x80080
	s_addc_u32 s21, s21, 0
	s_add_u32 s58, s22, 0x100
	v_mov_b32_e32 v0, 0
	s_addc_u32 s59, s23, 0
	s_mov_b32 s60, -2
	v_mov_b32_e32 v1, v0
	v_mov_b32_e32 v2, v0
	v_mov_b32_e32 v3, v0
	v_mov_b32_e32 v4, v0
	v_mov_b32_e32 v5, v0
	v_mov_b32_e32 v6, v0
	v_mov_b32_e32 v7, v0
	v_mov_b32_e32 v16, v0
	v_mov_b32_e32 v17, v0
	v_mov_b32_e32 v18, v0
	v_mov_b32_e32 v19, v0
	v_mov_b32_e32 v20, v0
	v_mov_b32_e32 v21, v0
	v_mov_b32_e32 v22, v0
	v_mov_b32_e32 v23, v0
	v_mov_b32_e32 v32, v0
	v_mov_b32_e32 v33, v0
	v_mov_b32_e32 v34, v0
	v_mov_b32_e32 v35, v0
	v_mov_b32_e32 v36, v0
	v_mov_b32_e32 v37, v0
	v_mov_b32_e32 v38, v0
	v_mov_b32_e32 v39, v0
	v_mov_b32_e32 v48, v0
	v_mov_b32_e32 v49, v0
	v_mov_b32_e32 v50, v0
	v_mov_b32_e32 v51, v0
	v_mov_b32_e32 v52, v0
	v_mov_b32_e32 v53, v0
	v_mov_b32_e32 v54, v0
	v_mov_b32_e32 v55, v0
	v_mov_b32_e32 v8, v0
	v_mov_b32_e32 v9, v0
	v_mov_b32_e32 v10, v0
	v_mov_b32_e32 v11, v0
	v_mov_b32_e32 v12, v0
	v_mov_b32_e32 v13, v0
	v_mov_b32_e32 v14, v0
	v_mov_b32_e32 v15, v0
	v_mov_b32_e32 v24, v0
	v_mov_b32_e32 v25, v0
	v_mov_b32_e32 v26, v0
	v_mov_b32_e32 v27, v0
	v_mov_b32_e32 v28, v0
	v_mov_b32_e32 v29, v0
	v_mov_b32_e32 v30, v0
	v_mov_b32_e32 v31, v0
	v_mov_b32_e32 v40, v0
	v_mov_b32_e32 v41, v0
	v_mov_b32_e32 v42, v0
	v_mov_b32_e32 v43, v0
	v_mov_b32_e32 v44, v0
	v_mov_b32_e32 v45, v0
	v_mov_b32_e32 v46, v0
	v_mov_b32_e32 v47, v0
	v_mov_b32_e32 v56, v0
	v_mov_b32_e32 v57, v0
	v_mov_b32_e32 v58, v0
	v_mov_b32_e32 v59, v0
	v_mov_b32_e32 v60, v0
	v_mov_b32_e32 v61, v0
	v_mov_b32_e32 v62, v0
	v_mov_b32_e32 v63, v0
	v_mov_b32_e32 v64, v0
	v_mov_b32_e32 v65, v0
	v_mov_b32_e32 v66, v0
	v_mov_b32_e32 v67, v0
	v_mov_b32_e32 v68, v0
	v_mov_b32_e32 v69, v0
	v_mov_b32_e32 v70, v0
	v_mov_b32_e32 v71, v0
	v_mov_b32_e32 v80, v0
	v_mov_b32_e32 v81, v0
	v_mov_b32_e32 v82, v0
	v_mov_b32_e32 v83, v0
	v_mov_b32_e32 v84, v0
	v_mov_b32_e32 v85, v0
	v_mov_b32_e32 v86, v0
	v_mov_b32_e32 v87, v0
	v_mov_b32_e32 v96, v0
	v_mov_b32_e32 v97, v0
	v_mov_b32_e32 v98, v0
	v_mov_b32_e32 v99, v0
	v_mov_b32_e32 v100, v0
	v_mov_b32_e32 v101, v0
	v_mov_b32_e32 v102, v0
	v_mov_b32_e32 v103, v0
	v_mov_b32_e32 v112, v0
	v_mov_b32_e32 v113, v0
	v_mov_b32_e32 v114, v0
	v_mov_b32_e32 v115, v0
	v_mov_b32_e32 v116, v0
	v_mov_b32_e32 v117, v0
	v_mov_b32_e32 v118, v0
	v_mov_b32_e32 v119, v0
	v_mov_b32_e32 v72, v0
	v_mov_b32_e32 v73, v0
	v_mov_b32_e32 v74, v0
	v_mov_b32_e32 v75, v0
	v_mov_b32_e32 v76, v0
	v_mov_b32_e32 v77, v0
	v_mov_b32_e32 v78, v0
	v_mov_b32_e32 v79, v0
	v_mov_b32_e32 v88, v0
	v_mov_b32_e32 v89, v0
	v_mov_b32_e32 v90, v0
	v_mov_b32_e32 v91, v0
	v_mov_b32_e32 v92, v0
	v_mov_b32_e32 v93, v0
	v_mov_b32_e32 v94, v0
	v_mov_b32_e32 v95, v0
	v_mov_b32_e32 v104, v0
	v_mov_b32_e32 v105, v0
	v_mov_b32_e32 v106, v0
	v_mov_b32_e32 v107, v0
	v_mov_b32_e32 v108, v0
	v_mov_b32_e32 v109, v0
	v_mov_b32_e32 v110, v0
	v_mov_b32_e32 v111, v0
	v_mov_b32_e32 v120, v0
	v_mov_b32_e32 v121, v0
	v_mov_b32_e32 v122, v0
	v_mov_b32_e32 v123, v0
	v_mov_b32_e32 v124, v0
	v_mov_b32_e32 v125, v0
	v_mov_b32_e32 v126, v0
	v_mov_b32_e32 v127, v0
	v_add_u32_e32 v230, 0x10000, v141
	v_add_u32_e32 v231, 0x14000, v141
	v_add_u32_e32 v232, 0x18000, v141
	v_add_u32_e32 v233, 0x1c000, v141
	s_add_u32 s22, s20, 0xfff80080
	s_addc_u32 s23, s21, -1
	s_add_i32 s61, 0, 0x10000
	s_cmp_eq_u32 s60, 28
	s_cselect_b32 s47, s35, s23
	s_cselect_b32 s46, s56, s22
	s_cselect_b32 s23, s25, s59
	s_cselect_b32 s22, s57, s58
	s_add_i32 m0, s5, 0xc000
.LBB0_773:
	ds_read_b128 v[144:147], v230
	ds_read_b128 v[148:151], v230 offset:1024
	ds_read_b128 v[162:165], v230 offset:2048
	ds_read_b128 v[166:169], v230 offset:3072
	ds_read_b128 v[170:173], v143
	ds_read_b128 v[174:177], v143 offset:1024
	ds_read_b128 v[178:181], v143 offset:2048
	ds_read_b128 v[182:185], v143 offset:3072
	ds_read_b128 v[186:189], v143 offset:4096
	ds_read_b128 v[190:193], v143 offset:5120
	ds_read_b128 v[206:209], v143 offset:6144
	ds_read_b128 v[210:213], v143 offset:7168
	global_load_lds_dwordx4 v134, s[20:21]
	s_add_i32 m0, s5, 0xe000
	s_nop 0
	global_load_lds_dwordx4 v136, s[20:21]
	s_waitcnt lgkmcnt(8)
	s_barrier
	s_waitcnt lgkmcnt(0)
	v_mfma_f32_16x16x32_bf16 v[124:127], v[144:147], v[170:173], v[124:127]
	v_mfma_f32_16x16x32_bf16 v[120:123], v[162:165], v[170:173], v[120:123]
	v_mfma_f32_16x16x32_bf16 v[108:111], v[144:147], v[178:181], v[108:111]
	v_mfma_f32_16x16x32_bf16 v[104:107], v[162:165], v[178:181], v[104:107]
	v_mfma_f32_16x16x32_bf16 v[92:95], v[144:147], v[186:189], v[92:95]
	v_mfma_f32_16x16x32_bf16 v[88:91], v[162:165], v[186:189], v[88:91]
	v_mfma_f32_16x16x32_bf16 v[76:79], v[144:147], v[206:209], v[76:79]
	v_mfma_f32_16x16x32_bf16 v[72:75], v[162:165], v[206:209], v[72:75]
	v_mfma_f32_16x16x32_bf16 v[124:127], v[148:151], v[174:177], v[124:127]
	v_mfma_f32_16x16x32_bf16 v[120:123], v[166:169], v[174:177], v[120:123]
	v_mfma_f32_16x16x32_bf16 v[108:111], v[148:151], v[182:185], v[108:111]
	v_mfma_f32_16x16x32_bf16 v[104:107], v[166:169], v[182:185], v[104:107]
	v_mfma_f32_16x16x32_bf16 v[92:95], v[148:151], v[190:193], v[92:95]
	v_mfma_f32_16x16x32_bf16 v[88:91], v[166:169], v[190:193], v[88:91]
	v_mfma_f32_16x16x32_bf16 v[76:79], v[148:151], v[210:213], v[76:79]
	v_mfma_f32_16x16x32_bf16 v[72:75], v[166:169], v[210:213], v[72:75]
	s_barrier
	s_add_i32 s68, 0, 0x14000
	s_add_i32 s61, s61, s4
	ds_read_b128 v[214:217], v231
	ds_read_b128 v[218:221], v231 offset:1024
	ds_read_b128 v[222:225], v231 offset:2048
	ds_read_b128 v[226:229], v231 offset:3072
	s_mov_b32 m0, s61
	s_nop 0
	global_load_lds_dwordx4 v152, s[22:23]
	s_add_i32 m0, s61, 0x2000
	s_nop 0
	global_load_lds_dwordx4 v132, s[22:23]
	s_barrier
	s_waitcnt lgkmcnt(0)
	v_mfma_f32_16x16x32_bf16 v[116:119], v[214:217], v[170:173], v[116:119]
	v_mfma_f32_16x16x32_bf16 v[112:115], v[222:225], v[170:173], v[112:115]
	v_mfma_f32_16x16x32_bf16 v[100:103], v[214:217], v[178:181], v[100:103]
	v_mfma_f32_16x16x32_bf16 v[96:99], v[222:225], v[178:181], v[96:99]
	v_mfma_f32_16x16x32_bf16 v[84:87], v[214:217], v[186:189], v[84:87]
	v_mfma_f32_16x16x32_bf16 v[80:83], v[222:225], v[186:189], v[80:83]
	v_mfma_f32_16x16x32_bf16 v[68:71], v[214:217], v[206:209], v[68:71]
	v_mfma_f32_16x16x32_bf16 v[64:67], v[222:225], v[206:209], v[64:67]
	v_mfma_f32_16x16x32_bf16 v[116:119], v[218:221], v[174:177], v[116:119]
	v_mfma_f32_16x16x32_bf16 v[112:115], v[226:229], v[174:177], v[112:115]
	v_mfma_f32_16x16x32_bf16 v[100:103], v[218:221], v[182:185], v[100:103]
	v_mfma_f32_16x16x32_bf16 v[96:99], v[226:229], v[182:185], v[96:99]
	v_mfma_f32_16x16x32_bf16 v[84:87], v[218:221], v[190:193], v[84:87]
	v_mfma_f32_16x16x32_bf16 v[80:83], v[226:229], v[190:193], v[80:83]
	v_mfma_f32_16x16x32_bf16 v[68:71], v[218:221], v[210:213], v[68:71]
	v_mfma_f32_16x16x32_bf16 v[64:67], v[226:229], v[210:213], v[64:67]
	s_barrier
	s_mov_b32 m0, s5
	s_add_u32 s98, s46, 0x80
	s_addc_u32 s99, s47, 0
	ds_read_b128 v[170:173], v143 offset:16384
	ds_read_b128 v[174:177], v143 offset:17408
	ds_read_b128 v[178:181], v143 offset:18432
	ds_read_b128 v[182:185], v143 offset:19456
	ds_read_b128 v[186:189], v143 offset:20480
	ds_read_b128 v[190:193], v143 offset:21504
	ds_read_b128 v[206:209], v143 offset:22528
	ds_read_b128 v[210:213], v143 offset:23552
	global_load_lds_dwordx4 v128, s[46:47]
	s_mov_b32 m0, s50
	s_nop 0
	global_load_lds_dwordx4 v130, s[46:47]
	s_barrier
	s_waitcnt lgkmcnt(0)
	v_mfma_f32_16x16x32_bf16 v[60:63], v[144:147], v[170:173], v[60:63]
	v_mfma_f32_16x16x32_bf16 v[56:59], v[162:165], v[170:173], v[56:59]
	v_mfma_f32_16x16x32_bf16 v[44:47], v[144:147], v[178:181], v[44:47]
	v_mfma_f32_16x16x32_bf16 v[40:43], v[162:165], v[178:181], v[40:43]
	v_mfma_f32_16x16x32_bf16 v[28:31], v[144:147], v[186:189], v[28:31]
	v_mfma_f32_16x16x32_bf16 v[24:27], v[162:165], v[186:189], v[24:27]
	v_mfma_f32_16x16x32_bf16 v[12:15], v[144:147], v[206:209], v[12:15]
	v_mfma_f32_16x16x32_bf16 v[8:11], v[162:165], v[206:209], v[8:11]
	v_mfma_f32_16x16x32_bf16 v[60:63], v[148:151], v[174:177], v[60:63]
	v_mfma_f32_16x16x32_bf16 v[56:59], v[166:169], v[174:177], v[56:59]
	v_mfma_f32_16x16x32_bf16 v[44:47], v[148:151], v[182:185], v[44:47]
	v_mfma_f32_16x16x32_bf16 v[40:43], v[166:169], v[182:185], v[40:43]
	v_mfma_f32_16x16x32_bf16 v[28:31], v[148:151], v[190:193], v[28:31]
	v_mfma_f32_16x16x32_bf16 v[24:27], v[166:169], v[190:193], v[24:27]
	v_mfma_f32_16x16x32_bf16 v[12:15], v[148:151], v[210:213], v[12:15]
	v_mfma_f32_16x16x32_bf16 v[8:11], v[166:169], v[210:213], v[8:11]
	s_barrier
	s_add_u32 s62, s22, 0x80000
	s_addc_u32 s63, s23, 0
	s_add_i32 s61, s68, s4
	s_mov_b32 m0, s61
	s_nop 0
	global_load_lds_dwordx4 v152, s[62:63]
	s_add_i32 m0, s61, 0x2000
	s_nop 0
	global_load_lds_dwordx4 v132, s[62:63]
	s_add_i32 s61, 0, 0x18000
	s_add_u32 s46, s46, 0x80000
	s_addc_u32 s47, s47, 0
	s_mov_b32 m0, s51
	s_waitcnt vmcnt(6)
	s_barrier
	v_mfma_f32_16x16x32_bf16 v[52:55], v[214:217], v[170:173], v[52:55]
	v_mfma_f32_16x16x32_bf16 v[48:51], v[222:225], v[170:173], v[48:51]
	v_mfma_f32_16x16x32_bf16 v[36:39], v[214:217], v[178:181], v[36:39]
	v_mfma_f32_16x16x32_bf16 v[32:35], v[222:225], v[178:181], v[32:35]
	v_mfma_f32_16x16x32_bf16 v[20:23], v[214:217], v[186:189], v[20:23]
	v_mfma_f32_16x16x32_bf16 v[16:19], v[222:225], v[186:189], v[16:19]
	v_mfma_f32_16x16x32_bf16 v[4:7], v[214:217], v[206:209], v[4:7]
	v_mfma_f32_16x16x32_bf16 v[0:3], v[222:225], v[206:209], v[0:3]
	v_mfma_f32_16x16x32_bf16 v[52:55], v[218:221], v[174:177], v[52:55]
	v_mfma_f32_16x16x32_bf16 v[48:51], v[226:229], v[174:177], v[48:51]
	v_mfma_f32_16x16x32_bf16 v[36:39], v[218:221], v[182:185], v[36:39]
	v_mfma_f32_16x16x32_bf16 v[32:35], v[226:229], v[182:185], v[32:35]
	v_mfma_f32_16x16x32_bf16 v[20:23], v[218:221], v[190:193], v[20:23]
	v_mfma_f32_16x16x32_bf16 v[16:19], v[226:229], v[190:193], v[16:19]
	v_mfma_f32_16x16x32_bf16 v[4:7], v[218:221], v[210:213], v[4:7]
	v_mfma_f32_16x16x32_bf16 v[0:3], v[226:229], v[210:213], v[0:3]
	s_barrier
	ds_read_b128 v[144:147], v232
	ds_read_b128 v[148:151], v232 offset:1024
	ds_read_b128 v[162:165], v232 offset:2048
	ds_read_b128 v[166:169], v232 offset:3072
	ds_read_b128 v[170:173], v143 offset:32768
	ds_read_b128 v[174:177], v143 offset:33792
	ds_read_b128 v[178:181], v143 offset:34816
	ds_read_b128 v[182:185], v143 offset:35840
	ds_read_b128 v[186:189], v143 offset:36864
	ds_read_b128 v[190:193], v143 offset:37888
	ds_read_b128 v[206:209], v143 offset:38912
	ds_read_b128 v[210:213], v143 offset:39936
	global_load_lds_dwordx4 v128, s[46:47]
	s_mov_b32 m0, s52
	s_nop 0
	global_load_lds_dwordx4 v130, s[46:47]
	s_waitcnt lgkmcnt(8)
	s_barrier
	s_waitcnt lgkmcnt(0)
	v_mfma_f32_16x16x32_bf16 v[124:127], v[144:147], v[170:173], v[124:127]
	v_mfma_f32_16x16x32_bf16 v[120:123], v[162:165], v[170:173], v[120:123]
	v_mfma_f32_16x16x32_bf16 v[108:111], v[144:147], v[178:181], v[108:111]
	v_mfma_f32_16x16x32_bf16 v[104:107], v[162:165], v[178:181], v[104:107]
	v_mfma_f32_16x16x32_bf16 v[92:95], v[144:147], v[186:189], v[92:95]
	v_mfma_f32_16x16x32_bf16 v[88:91], v[162:165], v[186:189], v[88:91]
	v_mfma_f32_16x16x32_bf16 v[76:79], v[144:147], v[206:209], v[76:79]
	v_mfma_f32_16x16x32_bf16 v[72:75], v[162:165], v[206:209], v[72:75]
	v_mfma_f32_16x16x32_bf16 v[124:127], v[148:151], v[174:177], v[124:127]
	v_mfma_f32_16x16x32_bf16 v[120:123], v[166:169], v[174:177], v[120:123]
	v_mfma_f32_16x16x32_bf16 v[108:111], v[148:151], v[182:185], v[108:111]
	v_mfma_f32_16x16x32_bf16 v[104:107], v[166:169], v[182:185], v[104:107]
	v_mfma_f32_16x16x32_bf16 v[92:95], v[148:151], v[190:193], v[92:95]
	v_mfma_f32_16x16x32_bf16 v[88:91], v[166:169], v[190:193], v[88:91]
	v_mfma_f32_16x16x32_bf16 v[76:79], v[148:151], v[210:213], v[76:79]
	v_mfma_f32_16x16x32_bf16 v[72:75], v[166:169], v[210:213], v[72:75]
	s_barrier
	s_add_i32 s46, 0, 0x1c000
	s_add_i32 s47, s61, s4
	s_add_u32 s100, s22, 0x80
	s_addc_u32 s101, s23, 0
	s_mov_b32 m0, s47
	ds_read_b128 v[214:217], v233
	ds_read_b128 v[218:221], v233 offset:1024
	ds_read_b128 v[222:225], v233 offset:2048
	ds_read_b128 v[226:229], v233 offset:3072
	global_load_lds_dwordx4 v152, s[100:101]
	s_add_i32 m0, s47, 0x2000
	s_nop 0
	global_load_lds_dwordx4 v132, s[100:101]
	s_barrier
	s_waitcnt lgkmcnt(0)
	v_mfma_f32_16x16x32_bf16 v[116:119], v[214:217], v[170:173], v[116:119]
	v_mfma_f32_16x16x32_bf16 v[112:115], v[222:225], v[170:173], v[112:115]
	v_mfma_f32_16x16x32_bf16 v[100:103], v[214:217], v[178:181], v[100:103]
	v_mfma_f32_16x16x32_bf16 v[96:99], v[222:225], v[178:181], v[96:99]
	v_mfma_f32_16x16x32_bf16 v[84:87], v[214:217], v[186:189], v[84:87]
	v_mfma_f32_16x16x32_bf16 v[80:83], v[222:225], v[186:189], v[80:83]
	v_mfma_f32_16x16x32_bf16 v[68:71], v[214:217], v[206:209], v[68:71]
	v_mfma_f32_16x16x32_bf16 v[64:67], v[222:225], v[206:209], v[64:67]
	v_mfma_f32_16x16x32_bf16 v[116:119], v[218:221], v[174:177], v[116:119]
	v_mfma_f32_16x16x32_bf16 v[112:115], v[226:229], v[174:177], v[112:115]
	v_mfma_f32_16x16x32_bf16 v[100:103], v[218:221], v[182:185], v[100:103]
	v_mfma_f32_16x16x32_bf16 v[96:99], v[226:229], v[182:185], v[96:99]
	v_mfma_f32_16x16x32_bf16 v[84:87], v[218:221], v[190:193], v[84:87]
	v_mfma_f32_16x16x32_bf16 v[80:83], v[226:229], v[190:193], v[80:83]
	v_mfma_f32_16x16x32_bf16 v[68:71], v[218:221], v[210:213], v[68:71]
	v_mfma_f32_16x16x32_bf16 v[64:67], v[226:229], v[210:213], v[64:67]
	s_barrier
	s_mov_b32 m0, s53
	ds_read_b128 v[170:173], v143 offset:49152
	ds_read_b128 v[174:177], v143 offset:50176
	ds_read_b128 v[178:181], v143 offset:51200
	ds_read_b128 v[182:185], v143 offset:52224
	ds_read_b128 v[186:189], v143 offset:53248
	ds_read_b128 v[190:193], v143 offset:54272
	ds_read_b128 v[206:209], v143 offset:55296
	ds_read_b128 v[210:213], v143 offset:56320
	global_load_lds_dwordx4 v128, s[98:99]
	s_mov_b32 m0, s54
	s_nop 0
	global_load_lds_dwordx4 v130, s[98:99]
	s_barrier
	s_waitcnt lgkmcnt(0)
	v_mfma_f32_16x16x32_bf16 v[60:63], v[144:147], v[170:173], v[60:63]
	v_mfma_f32_16x16x32_bf16 v[56:59], v[162:165], v[170:173], v[56:59]
	v_mfma_f32_16x16x32_bf16 v[44:47], v[144:147], v[178:181], v[44:47]
	v_mfma_f32_16x16x32_bf16 v[40:43], v[162:165], v[178:181], v[40:43]
	v_mfma_f32_16x16x32_bf16 v[28:31], v[144:147], v[186:189], v[28:31]
	v_mfma_f32_16x16x32_bf16 v[24:27], v[162:165], v[186:189], v[24:27]
	v_mfma_f32_16x16x32_bf16 v[12:15], v[144:147], v[206:209], v[12:15]
	v_mfma_f32_16x16x32_bf16 v[8:11], v[162:165], v[206:209], v[8:11]
	v_mfma_f32_16x16x32_bf16 v[60:63], v[148:151], v[174:177], v[60:63]
	v_mfma_f32_16x16x32_bf16 v[56:59], v[166:169], v[174:177], v[56:59]
	v_mfma_f32_16x16x32_bf16 v[44:47], v[148:151], v[182:185], v[44:47]
	v_mfma_f32_16x16x32_bf16 v[40:43], v[166:169], v[182:185], v[40:43]
	v_mfma_f32_16x16x32_bf16 v[28:31], v[148:151], v[190:193], v[28:31]
	v_mfma_f32_16x16x32_bf16 v[24:27], v[166:169], v[190:193], v[24:27]
	v_mfma_f32_16x16x32_bf16 v[12:15], v[148:151], v[210:213], v[12:15]
	v_mfma_f32_16x16x32_bf16 v[8:11], v[166:169], v[210:213], v[8:11]
	s_barrier
	s_add_u32 s22, s22, 0x80080
	s_addc_u32 s23, s23, 0
	s_add_i32 s46, s46, s4
	s_mov_b32 m0, s46
	s_nop 0
	global_load_lds_dwordx4 v152, s[22:23]
	s_add_i32 m0, s46, 0x2000
	s_nop 0
	global_load_lds_dwordx4 v132, s[22:23]
	s_add_i32 s60, s60, 2
	s_add_u32 s20, s20, 0x100
	s_addc_u32 s21, s21, 0
	s_add_u32 s58, s58, 0x100
	s_addc_u32 s59, s59, 0
	s_add_u32 s22, s20, 0xfff80080
	s_addc_u32 s23, s21, -1
	s_add_i32 s61, 0, 0x10000
	s_cmp_eq_u32 s60, 28
	s_cselect_b32 s47, s35, s23
	s_cselect_b32 s46, s56, s22
	s_cselect_b32 s23, s25, s59
	s_cselect_b32 s22, s57, s58
	s_add_i32 m0, s5, 0xc000
	s_cmp_gt_u32 s60, 29
	s_waitcnt vmcnt(6)
	s_barrier
	v_mfma_f32_16x16x32_bf16 v[52:55], v[214:217], v[170:173], v[52:55]
	v_mfma_f32_16x16x32_bf16 v[48:51], v[222:225], v[170:173], v[48:51]
	v_mfma_f32_16x16x32_bf16 v[36:39], v[214:217], v[178:181], v[36:39]
	v_mfma_f32_16x16x32_bf16 v[32:35], v[222:225], v[178:181], v[32:35]
	v_mfma_f32_16x16x32_bf16 v[20:23], v[214:217], v[186:189], v[20:23]
	v_mfma_f32_16x16x32_bf16 v[16:19], v[222:225], v[186:189], v[16:19]
	v_mfma_f32_16x16x32_bf16 v[4:7], v[214:217], v[206:209], v[4:7]
	v_mfma_f32_16x16x32_bf16 v[0:3], v[222:225], v[206:209], v[0:3]
	v_mfma_f32_16x16x32_bf16 v[52:55], v[218:221], v[174:177], v[52:55]
	v_mfma_f32_16x16x32_bf16 v[48:51], v[226:229], v[174:177], v[48:51]
	v_mfma_f32_16x16x32_bf16 v[36:39], v[218:221], v[182:185], v[36:39]
	v_mfma_f32_16x16x32_bf16 v[32:35], v[226:229], v[182:185], v[32:35]
	v_mfma_f32_16x16x32_bf16 v[20:23], v[218:221], v[190:193], v[20:23]
	v_mfma_f32_16x16x32_bf16 v[16:19], v[226:229], v[190:193], v[16:19]
	v_mfma_f32_16x16x32_bf16 v[4:7], v[218:221], v[210:213], v[4:7]
	v_mfma_f32_16x16x32_bf16 v[0:3], v[226:229], v[210:213], v[0:3]
	s_barrier
	s_cbranch_scc0 .LBB0_773
	v_lshl_add_u32 v144, s7, 8, v140
	v_max_f32_e32 v120, v120, v120
	v_ashrrev_i32_e32 v145, 31, v144
	v_max_f32_e32 v120, 0, v120
	v_max_f32_e32 v121, v121, v121
	v_max_f32_e32 v122, v122, v122
	v_lshl_or_b32 v138, s6, 8, v142
	v_lshlrev_b64 v[146:147], 14, v[144:145]
	v_mul_f32_e32 v145, v120, v120
	v_max_f32_e32 v120, v125, v125
	v_max_f32_e32 v121, 0, v121
	v_max_f32_e32 v122, 0, v122
	v_ashrrev_i32_e32 v139, 31, v138
	v_max_f32_e32 v124, v124, v124
	v_max_f32_e32 v120, 0, v120
	v_mul_f32_e32 v125, v121, v121
	v_max_f32_e32 v121, v126, v126
	v_mul_f32_e32 v126, v122, v122
	v_max_f32_e32 v122, v127, v127
	v_max_f32_e32 v123, v123, v123
	v_lshl_add_u64 v[146:147], s[16:17], 0, v[146:147]
	v_lshlrev_b64 v[148:149], 1, v[138:139]
	v_max_f32_e32 v124, 0, v124
	v_mul_f32_e32 v120, v120, v120
	v_max_f32_e32 v121, 0, v121
	v_max_f32_e32 v122, 0, v122
	v_max_f32_e32 v123, 0, v123
	v_max_f32_e32 v112, v112, v112
	v_lshl_add_u64 v[138:139], v[146:147], 0, v[148:149]
	v_mul_f32_e32 v124, v124, v124
	v_mul_f32_e32 v121, v121, v121
	v_mul_f32_e32 v122, v122, v122
	v_mul_f32_e32 v123, v123, v123
	v_cvt_pk_bf16_f32 v120, v124, v120
	v_max_f32_e32 v112, 0, v112
	v_max_f32_e32 v113, v113, v113
	v_max_f32_e32 v114, v114, v114
	v_cvt_pk_bf16_f32 v121, v121, v122
	v_cvt_pk_bf16_f32 v122, v145, v125
	v_cvt_pk_bf16_f32 v123, v126, v123
	global_store_dwordx4 v[138:139], v[120:123], off
	v_max_f32_e32 v113, 0, v113
	v_max_f32_e32 v114, 0, v114
	v_mul_f32_e32 v120, v112, v112
	v_max_f32_e32 v112, v117, v117
	v_max_f32_e32 v116, v116, v116
	v_max_f32_e32 v112, 0, v112
	v_mul_f32_e32 v117, v113, v113
	v_max_f32_e32 v113, v118, v118
	v_mul_f32_e32 v118, v114, v114
	v_max_f32_e32 v114, v119, v119
	v_max_f32_e32 v115, v115, v115
	v_max_f32_e32 v116, 0, v116
	v_mul_f32_e32 v112, v112, v112
	v_max_f32_e32 v113, 0, v113
	v_max_f32_e32 v114, 0, v114
	v_max_f32_e32 v115, 0, v115
	v_mul_f32_e32 v116, v116, v116
	v_mul_f32_e32 v113, v113, v113
	v_mul_f32_e32 v114, v114, v114
	v_mul_f32_e32 v115, v115, v115
	v_cvt_pk_bf16_f32 v112, v116, v112
	v_max_f32_e32 v104, v104, v104
	v_cvt_pk_bf16_f32 v113, v113, v114
	v_cvt_pk_bf16_f32 v114, v120, v117
	v_cvt_pk_bf16_f32 v115, v118, v115
	global_store_dwordx4 v[138:139], v[112:115], off offset:256
	v_max_f32_e32 v104, 0, v104
	v_max_f32_e32 v105, v105, v105
	v_or_b32_e32 v112, 16, v144
	v_max_f32_e32 v106, v106, v106
	v_ashrrev_i32_e32 v113, 31, v112
	v_mul_f32_e32 v114, v104, v104
	v_max_f32_e32 v104, v109, v109
	v_max_f32_e32 v105, 0, v105
	v_max_f32_e32 v106, 0, v106
	v_lshlrev_b64 v[112:113], 14, v[112:113]
	v_max_f32_e32 v108, v108, v108
	v_max_f32_e32 v104, 0, v104
	v_mul_f32_e32 v109, v105, v105
	v_max_f32_e32 v105, v110, v110
	v_mul_f32_e32 v110, v106, v106
	v_max_f32_e32 v106, v111, v111
	v_max_f32_e32 v107, v107, v107
	v_lshl_add_u64 v[112:113], s[16:17], 0, v[112:113]
	v_max_f32_e32 v108, 0, v108
	v_mul_f32_e32 v104, v104, v104
	v_max_f32_e32 v105, 0, v105
	v_max_f32_e32 v106, 0, v106
	v_max_f32_e32 v107, 0, v107
	v_max_f32_e32 v96, v96, v96
	v_lshl_add_u64 v[112:113], v[112:113], 0, v[148:149]
	v_mul_f32_e32 v108, v108, v108
	v_mul_f32_e32 v105, v105, v105
	v_mul_f32_e32 v106, v106, v106
	v_mul_f32_e32 v107, v107, v107
	v_cvt_pk_bf16_f32 v104, v108, v104
	v_max_f32_e32 v96, 0, v96
	v_max_f32_e32 v97, v97, v97
	v_max_f32_e32 v98, v98, v98
	v_cvt_pk_bf16_f32 v105, v105, v106
	v_cvt_pk_bf16_f32 v106, v114, v109
	v_cvt_pk_bf16_f32 v107, v110, v107
	global_store_dwordx4 v[112:113], v[104:107], off
	v_max_f32_e32 v97, 0, v97
	v_max_f32_e32 v98, 0, v98
	v_mul_f32_e32 v104, v96, v96
	v_max_f32_e32 v96, v101, v101
	v_max_f32_e32 v100, v100, v100
	v_max_f32_e32 v96, 0, v96
	v_mul_f32_e32 v101, v97, v97
	v_max_f32_e32 v97, v102, v102
	v_mul_f32_e32 v102, v98, v98
	v_max_f32_e32 v98, v103, v103
	v_max_f32_e32 v99, v99, v99
	v_max_f32_e32 v100, 0, v100
	v_mul_f32_e32 v96, v96, v96
	v_max_f32_e32 v97, 0, v97
	v_max_f32_e32 v98, 0, v98
	v_max_f32_e32 v99, 0, v99
	v_mul_f32_e32 v100, v100, v100
	v_mul_f32_e32 v97, v97, v97
	v_mul_f32_e32 v98, v98, v98
	v_mul_f32_e32 v99, v99, v99
	v_cvt_pk_bf16_f32 v96, v100, v96
	v_max_f32_e32 v88, v88, v88
	v_cvt_pk_bf16_f32 v97, v97, v98
	v_cvt_pk_bf16_f32 v98, v104, v101
	v_cvt_pk_bf16_f32 v99, v102, v99
	global_store_dwordx4 v[112:113], v[96:99], off offset:256
	v_max_f32_e32 v88, 0, v88
	v_max_f32_e32 v89, v89, v89
	v_or_b32_e32 v96, 32, v144
	v_max_f32_e32 v90, v90, v90
	v_ashrrev_i32_e32 v97, 31, v96
	v_mul_f32_e32 v98, v88, v88
	v_max_f32_e32 v88, v93, v93
	v_max_f32_e32 v89, 0, v89
	v_max_f32_e32 v90, 0, v90
	v_lshlrev_b64 v[96:97], 14, v[96:97]
	v_max_f32_e32 v92, v92, v92
	v_max_f32_e32 v88, 0, v88
	v_mul_f32_e32 v93, v89, v89
	v_max_f32_e32 v89, v94, v94
	v_mul_f32_e32 v94, v90, v90
	v_max_f32_e32 v90, v95, v95
	v_max_f32_e32 v91, v91, v91
	v_lshl_add_u64 v[96:97], s[16:17], 0, v[96:97]
	v_max_f32_e32 v92, 0, v92
	v_mul_f32_e32 v88, v88, v88
	v_max_f32_e32 v89, 0, v89
	v_max_f32_e32 v90, 0, v90
	v_max_f32_e32 v91, 0, v91
	v_max_f32_e32 v80, v80, v80
	v_lshl_add_u64 v[96:97], v[96:97], 0, v[148:149]
	v_mul_f32_e32 v92, v92, v92
	v_mul_f32_e32 v89, v89, v89
	v_mul_f32_e32 v90, v90, v90
	v_mul_f32_e32 v91, v91, v91
	v_cvt_pk_bf16_f32 v88, v92, v88
	v_max_f32_e32 v80, 0, v80
	v_max_f32_e32 v81, v81, v81
	v_max_f32_e32 v82, v82, v82
	v_cvt_pk_bf16_f32 v89, v89, v90
	v_cvt_pk_bf16_f32 v90, v98, v93
	v_cvt_pk_bf16_f32 v91, v94, v91
	global_store_dwordx4 v[96:97], v[88:91], off
	v_max_f32_e32 v81, 0, v81
	v_max_f32_e32 v82, 0, v82
	v_mul_f32_e32 v88, v80, v80
	v_max_f32_e32 v80, v85, v85
	v_max_f32_e32 v84, v84, v84
	v_max_f32_e32 v80, 0, v80
	v_mul_f32_e32 v85, v81, v81
	v_max_f32_e32 v81, v86, v86
	v_mul_f32_e32 v86, v82, v82
	v_max_f32_e32 v82, v87, v87
	v_max_f32_e32 v83, v83, v83
	v_max_f32_e32 v84, 0, v84
	v_mul_f32_e32 v80, v80, v80
	v_max_f32_e32 v81, 0, v81
	v_max_f32_e32 v82, 0, v82
	v_max_f32_e32 v83, 0, v83
	v_mul_f32_e32 v84, v84, v84
	v_mul_f32_e32 v81, v81, v81
	v_mul_f32_e32 v82, v82, v82
	v_mul_f32_e32 v83, v83, v83
	v_cvt_pk_bf16_f32 v80, v84, v80
	v_max_f32_e32 v72, v72, v72
	v_cvt_pk_bf16_f32 v81, v81, v82
	v_cvt_pk_bf16_f32 v82, v88, v85
	v_cvt_pk_bf16_f32 v83, v86, v83
	global_store_dwordx4 v[96:97], v[80:83], off offset:256
	v_max_f32_e32 v72, 0, v72
	v_max_f32_e32 v73, v73, v73
	v_or_b32_e32 v80, 48, v144
	v_max_f32_e32 v74, v74, v74
	v_ashrrev_i32_e32 v81, 31, v80
	v_mul_f32_e32 v82, v72, v72
	v_max_f32_e32 v72, v77, v77
	v_max_f32_e32 v73, 0, v73
	v_max_f32_e32 v74, 0, v74
	v_lshlrev_b64 v[80:81], 14, v[80:81]
	v_max_f32_e32 v76, v76, v76
	v_max_f32_e32 v72, 0, v72
	v_mul_f32_e32 v77, v73, v73
	v_max_f32_e32 v73, v78, v78
	v_mul_f32_e32 v78, v74, v74
	v_max_f32_e32 v74, v79, v79
	v_max_f32_e32 v75, v75, v75
	v_lshl_add_u64 v[80:81], s[16:17], 0, v[80:81]
	v_max_f32_e32 v76, 0, v76
	v_mul_f32_e32 v72, v72, v72
	v_max_f32_e32 v73, 0, v73
	v_max_f32_e32 v74, 0, v74
	v_max_f32_e32 v75, 0, v75
	v_max_f32_e32 v64, v64, v64
	v_max_f32_e32 v65, v65, v65
	v_max_f32_e32 v66, v66, v66
	v_lshl_add_u64 v[80:81], v[80:81], 0, v[148:149]
	v_mul_f32_e32 v76, v76, v76
	v_mul_f32_e32 v73, v73, v73
	v_mul_f32_e32 v74, v74, v74
	v_mul_f32_e32 v75, v75, v75
	v_cvt_pk_bf16_f32 v72, v76, v72
	v_max_f32_e32 v64, 0, v64
	v_max_f32_e32 v65, 0, v65
	v_max_f32_e32 v66, 0, v66
	v_cvt_pk_bf16_f32 v73, v73, v74
	v_cvt_pk_bf16_f32 v74, v82, v77
	v_cvt_pk_bf16_f32 v75, v78, v75
	global_store_dwordx4 v[80:81], v[72:75], off
	v_max_f32_e32 v68, v68, v68
	v_max_f32_e32 v67, v67, v67
	v_mul_f32_e32 v72, v64, v64
	v_max_f32_e32 v64, v69, v69
	v_mul_f32_e32 v69, v65, v65
	v_max_f32_e32 v65, v70, v70
	v_mul_f32_e32 v70, v66, v66
	v_max_f32_e32 v66, v71, v71
	v_max_f32_e32 v64, 0, v64
	v_max_f32_e32 v65, 0, v65
	v_max_f32_e32 v66, 0, v66
	v_max_f32_e32 v68, 0, v68
	v_mul_f32_e32 v64, v64, v64
	v_mul_f32_e32 v65, v65, v65
	v_max_f32_e32 v67, 0, v67
	v_mul_f32_e32 v66, v66, v66
	v_max_f32_e32 v56, v56, v56
	v_mul_f32_e32 v68, v68, v68
	v_mul_f32_e32 v67, v67, v67
	v_cvt_pk_bf16_f32 v64, v68, v64
	v_cvt_pk_bf16_f32 v65, v65, v66
	v_cvt_pk_bf16_f32 v66, v72, v69
	v_max_f32_e32 v56, 0, v56
	v_max_f32_e32 v57, v57, v57
	v_max_f32_e32 v58, v58, v58
	v_cvt_pk_bf16_f32 v67, v70, v67
	global_store_dwordx4 v[80:81], v[64:67], off offset:256
	v_max_f32_e32 v60, v60, v60
	v_max_f32_e32 v57, 0, v57
	v_mul_f32_e32 v66, v56, v56
	v_max_f32_e32 v56, v61, v61
	v_max_f32_e32 v58, 0, v58
	s_mov_b64 s[6:7], 0x200000
	v_max_f32_e32 v60, 0, v60
	v_max_f32_e32 v56, 0, v56
	v_mul_f32_e32 v61, v57, v57
	v_max_f32_e32 v57, v62, v62
	v_mul_f32_e32 v62, v58, v58
	v_max_f32_e32 v58, v63, v63
	v_lshl_add_u64 v[64:65], v[138:139], 0, s[6:7]
	v_mul_f32_e32 v60, v60, v60
	v_mul_f32_e32 v56, v56, v56
	v_max_f32_e32 v57, 0, v57
	v_max_f32_e32 v58, 0, v58
	v_max_f32_e32 v59, v59, v59
	s_mov_b32 s6, 0x200000
	v_mul_f32_e32 v57, v57, v57
	v_max_f32_e32 v59, 0, v59
	v_mul_f32_e32 v58, v58, v58
	v_cvt_pk_bf16_f32 v56, v60, v56
	v_add_co_u32_e32 v60, vcc, s6, v138
	v_max_f32_e32 v48, v48, v48
	v_max_f32_e32 v49, v49, v49
	v_max_f32_e32 v50, v50, v50
	v_mul_f32_e32 v59, v59, v59
	v_cvt_pk_bf16_f32 v57, v57, v58
	v_cvt_pk_bf16_f32 v58, v66, v61
	v_addc_co_u32_e32 v61, vcc, 0, v139, vcc
	v_max_f32_e32 v48, 0, v48
	v_max_f32_e32 v49, 0, v49
	v_max_f32_e32 v50, 0, v50
	v_cvt_pk_bf16_f32 v59, v62, v59
	global_store_dwordx4 v[60:61], v[56:59], off
	v_max_f32_e32 v52, v52, v52
	v_max_f32_e32 v51, v51, v51
	v_mul_f32_e32 v56, v48, v48
	v_max_f32_e32 v48, v53, v53
	v_mul_f32_e32 v53, v49, v49
	v_max_f32_e32 v49, v54, v54
	v_mul_f32_e32 v54, v50, v50
	v_max_f32_e32 v50, v55, v55
	v_max_f32_e32 v48, 0, v48
	v_max_f32_e32 v49, 0, v49
	v_max_f32_e32 v50, 0, v50
	v_max_f32_e32 v52, 0, v52
	v_mul_f32_e32 v48, v48, v48
	v_mul_f32_e32 v49, v49, v49
	v_max_f32_e32 v51, 0, v51
	v_mul_f32_e32 v50, v50, v50
	v_max_f32_e32 v40, v40, v40
	v_mul_f32_e32 v52, v52, v52
	v_mul_f32_e32 v51, v51, v51
	v_cvt_pk_bf16_f32 v48, v52, v48
	v_cvt_pk_bf16_f32 v49, v49, v50
	v_cvt_pk_bf16_f32 v50, v56, v53
	v_max_f32_e32 v40, 0, v40
	v_max_f32_e32 v41, v41, v41
	v_max_f32_e32 v42, v42, v42
	v_cvt_pk_bf16_f32 v51, v54, v51
	global_store_dwordx4 v[64:65], v[48:51], off offset:256
	v_max_f32_e32 v44, v44, v44
	v_max_f32_e32 v41, 0, v41
	v_mul_f32_e32 v50, v40, v40
	v_max_f32_e32 v40, v45, v45
	v_max_f32_e32 v42, 0, v42
	s_mov_b64 s[6:7], 0x240000
	v_max_f32_e32 v44, 0, v44
	v_max_f32_e32 v40, 0, v40
	v_mul_f32_e32 v45, v41, v41
	v_max_f32_e32 v41, v46, v46
	v_mul_f32_e32 v46, v42, v42
	v_max_f32_e32 v42, v47, v47
	v_lshl_add_u64 v[48:49], v[138:139], 0, s[6:7]
	v_mul_f32_e32 v44, v44, v44
	v_mul_f32_e32 v40, v40, v40
	v_max_f32_e32 v41, 0, v41
	v_max_f32_e32 v42, 0, v42
	v_max_f32_e32 v43, v43, v43
	s_mov_b32 s6, 0x240000
	v_mul_f32_e32 v41, v41, v41
	v_max_f32_e32 v43, 0, v43
	v_mul_f32_e32 v42, v42, v42
	v_cvt_pk_bf16_f32 v40, v44, v40
	v_add_co_u32_e32 v44, vcc, s6, v138
	v_max_f32_e32 v32, v32, v32
	v_max_f32_e32 v33, v33, v33
	v_max_f32_e32 v34, v34, v34
	v_mul_f32_e32 v43, v43, v43
	v_cvt_pk_bf16_f32 v41, v41, v42
	v_cvt_pk_bf16_f32 v42, v50, v45
	v_addc_co_u32_e32 v45, vcc, 0, v139, vcc
	v_max_f32_e32 v32, 0, v32
	v_max_f32_e32 v33, 0, v33
	v_max_f32_e32 v34, 0, v34
	v_cvt_pk_bf16_f32 v43, v46, v43
	global_store_dwordx4 v[44:45], v[40:43], off
	v_max_f32_e32 v36, v36, v36
	v_max_f32_e32 v35, v35, v35
	v_mul_f32_e32 v40, v32, v32
	v_max_f32_e32 v32, v37, v37
	v_mul_f32_e32 v37, v33, v33
	v_max_f32_e32 v33, v38, v38
	v_mul_f32_e32 v38, v34, v34
	v_max_f32_e32 v34, v39, v39
	v_max_f32_e32 v32, 0, v32
	v_max_f32_e32 v33, 0, v33
	v_max_f32_e32 v34, 0, v34
	v_max_f32_e32 v36, 0, v36
	v_mul_f32_e32 v32, v32, v32
	v_mul_f32_e32 v33, v33, v33
	v_max_f32_e32 v35, 0, v35
	v_mul_f32_e32 v34, v34, v34
	v_max_f32_e32 v24, v24, v24
	v_mul_f32_e32 v36, v36, v36
	v_mul_f32_e32 v35, v35, v35
	v_cvt_pk_bf16_f32 v32, v36, v32
	v_cvt_pk_bf16_f32 v33, v33, v34
	v_cvt_pk_bf16_f32 v34, v40, v37
	v_max_f32_e32 v24, 0, v24
	v_max_f32_e32 v25, v25, v25
	v_max_f32_e32 v26, v26, v26
	v_cvt_pk_bf16_f32 v35, v38, v35
	global_store_dwordx4 v[48:49], v[32:35], off offset:256
	v_max_f32_e32 v28, v28, v28
	v_max_f32_e32 v25, 0, v25
	v_mul_f32_e32 v34, v24, v24
	v_max_f32_e32 v24, v29, v29
	v_max_f32_e32 v26, 0, v26
	s_mov_b64 s[6:7], 0x280000
	v_max_f32_e32 v28, 0, v28
	v_max_f32_e32 v24, 0, v24
	v_mul_f32_e32 v29, v25, v25
	v_max_f32_e32 v25, v30, v30
	v_mul_f32_e32 v30, v26, v26
	v_max_f32_e32 v26, v31, v31
	v_lshl_add_u64 v[32:33], v[138:139], 0, s[6:7]
	v_mul_f32_e32 v28, v28, v28
	v_mul_f32_e32 v24, v24, v24
	v_max_f32_e32 v25, 0, v25
	v_max_f32_e32 v26, 0, v26
	v_max_f32_e32 v27, v27, v27
	s_mov_b32 s6, 0x280000
	v_mul_f32_e32 v25, v25, v25
	v_max_f32_e32 v27, 0, v27
	v_mul_f32_e32 v26, v26, v26
	v_cvt_pk_bf16_f32 v24, v28, v24
	v_add_co_u32_e32 v28, vcc, s6, v138
	v_max_f32_e32 v16, v16, v16
	v_max_f32_e32 v17, v17, v17
	v_max_f32_e32 v18, v18, v18
	v_mul_f32_e32 v27, v27, v27
	v_cvt_pk_bf16_f32 v25, v25, v26
	v_cvt_pk_bf16_f32 v26, v34, v29
	v_addc_co_u32_e32 v29, vcc, 0, v139, vcc
	v_max_f32_e32 v16, 0, v16
	v_max_f32_e32 v17, 0, v17
	v_max_f32_e32 v18, 0, v18
	v_cvt_pk_bf16_f32 v27, v30, v27
	global_store_dwordx4 v[28:29], v[24:27], off
	v_max_f32_e32 v20, v20, v20
	v_max_f32_e32 v19, v19, v19
	v_mul_f32_e32 v24, v16, v16
	v_max_f32_e32 v16, v21, v21
	v_mul_f32_e32 v21, v17, v17
	v_max_f32_e32 v17, v22, v22
	v_mul_f32_e32 v22, v18, v18
	v_max_f32_e32 v18, v23, v23
	v_max_f32_e32 v16, 0, v16
	v_max_f32_e32 v17, 0, v17
	v_max_f32_e32 v18, 0, v18
	v_max_f32_e32 v20, 0, v20
	v_mul_f32_e32 v16, v16, v16
	v_mul_f32_e32 v17, v17, v17
	v_max_f32_e32 v19, 0, v19
	v_mul_f32_e32 v18, v18, v18
	v_max_f32_e32 v8, v8, v8
	v_mul_f32_e32 v20, v20, v20
	v_mul_f32_e32 v19, v19, v19
	v_cvt_pk_bf16_f32 v16, v20, v16
	v_cvt_pk_bf16_f32 v17, v17, v18
	v_cvt_pk_bf16_f32 v18, v24, v21
	v_max_f32_e32 v8, 0, v8
	v_max_f32_e32 v9, v9, v9
	v_max_f32_e32 v10, v10, v10
	v_cvt_pk_bf16_f32 v19, v22, v19
	global_store_dwordx4 v[32:33], v[16:19], off offset:256
	v_max_f32_e32 v12, v12, v12
	v_max_f32_e32 v9, 0, v9
	v_mul_f32_e32 v18, v8, v8
	v_max_f32_e32 v8, v13, v13
	v_max_f32_e32 v10, 0, v10
	s_mov_b64 s[6:7], 0x2c0000
	v_max_f32_e32 v12, 0, v12
	v_max_f32_e32 v8, 0, v8
	v_mul_f32_e32 v13, v9, v9
	v_max_f32_e32 v9, v14, v14
	v_mul_f32_e32 v14, v10, v10
	v_max_f32_e32 v10, v15, v15
	v_lshl_add_u64 v[16:17], v[138:139], 0, s[6:7]
	v_mul_f32_e32 v12, v12, v12
	v_mul_f32_e32 v8, v8, v8
	v_max_f32_e32 v9, 0, v9
	v_max_f32_e32 v10, 0, v10
	v_max_f32_e32 v11, v11, v11
	s_mov_b32 s6, 0x2c0000
	v_mul_f32_e32 v9, v9, v9
	v_max_f32_e32 v11, 0, v11
	v_mul_f32_e32 v10, v10, v10
	v_cvt_pk_bf16_f32 v8, v12, v8
	v_add_co_u32_e32 v12, vcc, s6, v138
	v_max_f32_e32 v0, v0, v0
	v_max_f32_e32 v1, v1, v1
	v_max_f32_e32 v2, v2, v2
	v_mul_f32_e32 v11, v11, v11
	v_cvt_pk_bf16_f32 v9, v9, v10
	v_cvt_pk_bf16_f32 v10, v18, v13
	v_addc_co_u32_e32 v13, vcc, 0, v139, vcc
	v_max_f32_e32 v0, 0, v0
	v_max_f32_e32 v1, 0, v1
	v_max_f32_e32 v2, 0, v2
	v_cvt_pk_bf16_f32 v11, v14, v11
	global_store_dwordx4 v[12:13], v[8:11], off
	v_max_f32_e32 v3, v3, v3
	v_max_f32_e32 v4, v4, v4
	v_mul_f32_e32 v8, v0, v0
	v_max_f32_e32 v0, v5, v5
	v_mul_f32_e32 v5, v1, v1
	v_max_f32_e32 v1, v6, v6
	v_mul_f32_e32 v6, v2, v2
	v_max_f32_e32 v2, v7, v7
	v_max_f32_e32 v0, 0, v0
	v_max_f32_e32 v1, 0, v1
	v_max_f32_e32 v2, 0, v2
	v_max_f32_e32 v3, 0, v3
	v_max_f32_e32 v4, 0, v4
	v_mul_f32_e32 v0, v0, v0
	v_mul_f32_e32 v1, v1, v1
	v_mul_f32_e32 v2, v2, v2
	v_mul_f32_e32 v3, v3, v3
	s_and_b64 vcc, exec, s[38:39]
	s_mov_b32 s6, s24
	s_mov_b32 s7, s34
	s_mov_b64 s[22:23], s[44:45]
	s_mov_b64 s[20:21], s[42:43]
	v_mul_f32_e32 v4, v4, v4
	v_cvt_pk_bf16_f32 v0, v4, v0
	v_cvt_pk_bf16_f32 v1, v1, v2
	v_cvt_pk_bf16_f32 v2, v8, v5
	v_cvt_pk_bf16_f32 v3, v6, v3
	global_store_dwordx4 v[16:17], v[0:3], off offset:256
	s_cbranch_vccz .LBB0_770
	s_waitcnt vmcnt(0)
	v_readlane_b32 s34, v253, 45
	s_cmpk_gt_u32 s14, 0xff
	v_readlane_b32 s35, v253, 46
	s_cbranch_scc1 .LBB0_777
	s_barrier

.LBB0_835:
	s_ashr_i32 s17, s16, 31
	s_lshl_b64 s[6:7], s[16:17], 22
	s_add_u32 s24, s41, s6
	v_cmp_lt_i64_e32 vcc, s[14:15], v[160:161]
	s_addc_u32 s25, s43, s7
	s_ashr_i32 s1, s0, 31
	s_lshl_b64 s[14:15], s[0:1], 22
	s_add_u32 s14, s49, s14
	s_addc_u32 s15, s50, s15
	s_cmp_ge_u32 s2, 0x80
	s_cselect_b32 s100, 0x2000, 0
	s_cmp_eq_u32 s62, 1
	s_cselect_b32 s100, s100, 0
	s_cmp_lg_u32 s98, 0
	s_cselect_b32 s100, s100, 0
	s_add_u32 s24, s24, s100
	s_addc_u32 s25, s25, 0
	s_add_u32 s14, s14, s100
	s_addc_u32 s15, s15, 0
	s_and_b64 s[6:7], vcc, exec
	s_cselect_b32 s6, s25, s21
	s_cselect_b32 s7, s24, s20
	s_and_b64 s[34:35], vcc, exec
	s_cselect_b32 s1, s15, s23
	s_cselect_b32 s17, s14, s22
	s_cmp_lt_u32 s2, 0x80
	s_cselect_b32 s99, 1, 2
	s_cmp_eq_u32 s62, s99
	s_cselect_b32 s99, s99, 0
	s_cmp_lg_u32 s98, 0
	s_cselect_b32 s99, s99, 0
	s_add_u32 s20, s20, 0x200080
	s_addc_u32 s21, s21, 0
	s_add_u32 s63, s22, 0x100
	v_mov_b32_e32 v0, 0
	s_addc_u32 s68, s23, 0
	s_cmp_lg_u32 s99, 0
	s_cselect_b32 s69, 62, -2
	v_mov_b32_e32 v1, v0
	v_mov_b32_e32 v2, v0
	v_mov_b32_e32 v3, v0
	v_mov_b32_e32 v4, v0
	v_mov_b32_e32 v5, v0
	v_mov_b32_e32 v6, v0
	v_mov_b32_e32 v7, v0
	v_mov_b32_e32 v12, v0
	v_mov_b32_e32 v13, v0
	v_mov_b32_e32 v14, v0
	v_mov_b32_e32 v15, v0
	v_mov_b32_e32 v20, v0
	v_mov_b32_e32 v21, v0
	v_mov_b32_e32 v22, v0
	v_mov_b32_e32 v23, v0
	v_mov_b32_e32 v28, v0
	v_mov_b32_e32 v29, v0
	v_mov_b32_e32 v30, v0
	v_mov_b32_e32 v31, v0
	v_mov_b32_e32 v36, v0
	v_mov_b32_e32 v37, v0
	v_mov_b32_e32 v38, v0
	v_mov_b32_e32 v39, v0
	v_mov_b32_e32 v44, v0
	v_mov_b32_e32 v45, v0
	v_mov_b32_e32 v46, v0
	v_mov_b32_e32 v47, v0
	v_mov_b32_e32 v52, v0
	v_mov_b32_e32 v53, v0
	v_mov_b32_e32 v54, v0
	v_mov_b32_e32 v55, v0
	v_mov_b32_e32 v8, v0
	v_mov_b32_e32 v9, v0
	v_mov_b32_e32 v10, v0
	v_mov_b32_e32 v11, v0
	v_mov_b32_e32 v16, v0
	v_mov_b32_e32 v17, v0
	v_mov_b32_e32 v18, v0
	v_mov_b32_e32 v19, v0
	v_mov_b32_e32 v24, v0
	v_mov_b32_e32 v25, v0
	v_mov_b32_e32 v26, v0
	v_mov_b32_e32 v27, v0
	v_mov_b32_e32 v32, v0
	v_mov_b32_e32 v33, v0
	v_mov_b32_e32 v34, v0
	v_mov_b32_e32 v35, v0
	v_mov_b32_e32 v40, v0
	v_mov_b32_e32 v41, v0
	v_mov_b32_e32 v42, v0
	v_mov_b32_e32 v43, v0
	v_mov_b32_e32 v48, v0
	v_mov_b32_e32 v49, v0
	v_mov_b32_e32 v50, v0
	v_mov_b32_e32 v51, v0
	v_mov_b32_e32 v56, v0
	v_mov_b32_e32 v57, v0
	v_mov_b32_e32 v58, v0
	v_mov_b32_e32 v59, v0
	v_mov_b32_e32 v60, v0
	v_mov_b32_e32 v61, v0
	v_mov_b32_e32 v62, v0
	v_mov_b32_e32 v63, v0
	v_mov_b32_e32 v64, v0
	v_mov_b32_e32 v65, v0
	v_mov_b32_e32 v66, v0
	v_mov_b32_e32 v67, v0
	v_mov_b32_e32 v68, v0
	v_mov_b32_e32 v69, v0
	v_mov_b32_e32 v70, v0
	v_mov_b32_e32 v71, v0
	v_mov_b32_e32 v76, v0
	v_mov_b32_e32 v77, v0
	v_mov_b32_e32 v78, v0
	v_mov_b32_e32 v79, v0
	v_mov_b32_e32 v84, v0
	v_mov_b32_e32 v85, v0
	v_mov_b32_e32 v86, v0
	v_mov_b32_e32 v87, v0
	v_mov_b32_e32 v92, v0
	v_mov_b32_e32 v93, v0
	v_mov_b32_e32 v94, v0
	v_mov_b32_e32 v95, v0
	v_mov_b32_e32 v100, v0
	v_mov_b32_e32 v101, v0
	v_mov_b32_e32 v102, v0
	v_mov_b32_e32 v103, v0
	v_mov_b32_e32 v108, v0
	v_mov_b32_e32 v109, v0
	v_mov_b32_e32 v110, v0
	v_mov_b32_e32 v111, v0
	v_mov_b32_e32 v116, v0
	v_mov_b32_e32 v117, v0
	v_mov_b32_e32 v118, v0
	v_mov_b32_e32 v119, v0
	v_mov_b32_e32 v72, v0
	v_mov_b32_e32 v73, v0
	v_mov_b32_e32 v74, v0
	v_mov_b32_e32 v75, v0
	v_mov_b32_e32 v80, v0
	v_mov_b32_e32 v81, v0
	v_mov_b32_e32 v82, v0
	v_mov_b32_e32 v83, v0
	v_mov_b32_e32 v88, v0
	v_mov_b32_e32 v89, v0
	v_mov_b32_e32 v90, v0
	v_mov_b32_e32 v91, v0
	v_mov_b32_e32 v96, v0
	v_mov_b32_e32 v97, v0
	v_mov_b32_e32 v98, v0
	v_mov_b32_e32 v99, v0
	v_mov_b32_e32 v104, v0
	v_mov_b32_e32 v105, v0
	v_mov_b32_e32 v106, v0
	v_mov_b32_e32 v107, v0
	v_mov_b32_e32 v112, v0
	v_mov_b32_e32 v113, v0
	v_mov_b32_e32 v114, v0
	v_mov_b32_e32 v115, v0
	v_mov_b32_e32 v128, v0
	v_mov_b32_e32 v129, v0
	v_mov_b32_e32 v130, v0
	v_mov_b32_e32 v131, v0
	v_mov_b32_e32 v140, v0
	v_mov_b32_e32 v141, v0
	v_mov_b32_e32 v142, v0
	v_mov_b32_e32 v143, v0
	v_writelane_b32 v246, s98, 0
	v_writelane_b32 v246, s99, 1
	v_add_u32_e32 v248, 0x10000, v183
	v_add_u32_e32 v249, 0x14000, v183
	v_add_u32_e32 v250, 0x18000, v183
	v_add_u32_e32 v251, 0x1c000, v183
	s_add_u32 s22, s20, 0xffe00080
	s_addc_u32 s23, s21, -1
	s_add_i32 s78, 0, 0x10000
	s_cmpk_eq_i32 s69, 0x7c
	s_cselect_b32 s35, s6, s23
	s_cselect_b32 s34, s7, s22
	s_cselect_b32 s23, s1, s68
	s_cselect_b32 s22, s17, s63
	s_add_i32 m0, s52, 0xc000
.LBB0_836:
	ds_read_b128 v[120:123], v248
	ds_read_b128 v[124:127], v248 offset:1024
	ds_read_b128 v[132:135], v248 offset:2048
	ds_read_b128 v[136:139], v248 offset:3072
	ds_read_b128 v[186:189], v185
	ds_read_b128 v[190:193], v185 offset:1024
	ds_read_b128 v[206:209], v185 offset:2048
	ds_read_b128 v[210:213], v185 offset:3072
	ds_read_b128 v[214:217], v185 offset:4096
	ds_read_b128 v[218:221], v185 offset:5120
	ds_read_b128 v[222:225], v185 offset:6144
	ds_read_b128 v[226:229], v185 offset:7168
	global_load_lds_dwordx4 v176, s[20:21]
	s_add_i32 m0, s52, 0xe000
	s_nop 0
	global_load_lds_dwordx4 v178, s[20:21]
	s_waitcnt lgkmcnt(8)
	s_barrier
	s_waitcnt lgkmcnt(0)
	v_mfma_f32_16x16x32_bf16 v[140:143], v[120:123], v[186:189], v[140:143]
	v_mfma_f32_16x16x32_bf16 v[128:131], v[132:135], v[186:189], v[128:131]
	v_mfma_f32_16x16x32_bf16 v[112:115], v[120:123], v[206:209], v[112:115]
	v_mfma_f32_16x16x32_bf16 v[104:107], v[132:135], v[206:209], v[104:107]
	v_mfma_f32_16x16x32_bf16 v[96:99], v[120:123], v[214:217], v[96:99]
	v_mfma_f32_16x16x32_bf16 v[88:91], v[132:135], v[214:217], v[88:91]
	v_mfma_f32_16x16x32_bf16 v[80:83], v[120:123], v[222:225], v[80:83]
	v_mfma_f32_16x16x32_bf16 v[72:75], v[132:135], v[222:225], v[72:75]
	v_mfma_f32_16x16x32_bf16 v[140:143], v[124:127], v[190:193], v[140:143]
	v_mfma_f32_16x16x32_bf16 v[128:131], v[136:139], v[190:193], v[128:131]
	v_mfma_f32_16x16x32_bf16 v[112:115], v[124:127], v[210:213], v[112:115]
	v_mfma_f32_16x16x32_bf16 v[104:107], v[136:139], v[210:213], v[104:107]
	v_mfma_f32_16x16x32_bf16 v[96:99], v[124:127], v[218:221], v[96:99]
	v_mfma_f32_16x16x32_bf16 v[88:91], v[136:139], v[218:221], v[88:91]
	v_mfma_f32_16x16x32_bf16 v[80:83], v[124:127], v[226:229], v[80:83]
	v_mfma_f32_16x16x32_bf16 v[72:75], v[136:139], v[226:229], v[72:75]
	s_barrier
	s_add_i32 s80, 0, 0x14000
	s_add_i32 s78, s78, s51
	ds_read_b128 v[230:233], v249
	ds_read_b128 v[234:237], v249 offset:1024
	ds_read_b128 v[238:241], v249 offset:2048
	ds_read_b128 v[242:245], v249 offset:3072
	s_mov_b32 m0, s78
	s_nop 0
	global_load_lds_dwordx4 v152, s[22:23]
	s_add_i32 m0, s78, 0x2000
	s_nop 0
	global_load_lds_dwordx4 v144, s[22:23]
	s_barrier
	s_waitcnt lgkmcnt(0)
	v_mfma_f32_16x16x32_bf16 v[116:119], v[230:233], v[186:189], v[116:119]
	v_mfma_f32_16x16x32_bf16 v[108:111], v[238:241], v[186:189], v[108:111]
	v_mfma_f32_16x16x32_bf16 v[100:103], v[230:233], v[206:209], v[100:103]
	v_mfma_f32_16x16x32_bf16 v[92:95], v[238:241], v[206:209], v[92:95]
	v_mfma_f32_16x16x32_bf16 v[84:87], v[230:233], v[214:217], v[84:87]
	v_mfma_f32_16x16x32_bf16 v[76:79], v[238:241], v[214:217], v[76:79]
	v_mfma_f32_16x16x32_bf16 v[68:71], v[230:233], v[222:225], v[68:71]
	v_mfma_f32_16x16x32_bf16 v[64:67], v[238:241], v[222:225], v[64:67]
	v_mfma_f32_16x16x32_bf16 v[116:119], v[234:237], v[190:193], v[116:119]
	v_mfma_f32_16x16x32_bf16 v[108:111], v[242:245], v[190:193], v[108:111]
	v_mfma_f32_16x16x32_bf16 v[100:103], v[234:237], v[210:213], v[100:103]
	v_mfma_f32_16x16x32_bf16 v[92:95], v[242:245], v[210:213], v[92:95]
	v_mfma_f32_16x16x32_bf16 v[84:87], v[234:237], v[218:221], v[84:87]
	v_mfma_f32_16x16x32_bf16 v[76:79], v[242:245], v[218:221], v[76:79]
	v_mfma_f32_16x16x32_bf16 v[68:71], v[234:237], v[226:229], v[68:71]
	v_mfma_f32_16x16x32_bf16 v[64:67], v[242:245], v[226:229], v[64:67]
	s_barrier
	s_mov_b32 m0, s52
	s_add_u32 s98, s34, 0x80
	s_addc_u32 s99, s35, 0
	ds_read_b128 v[186:189], v185 offset:16384
	ds_read_b128 v[190:193], v185 offset:17408
	ds_read_b128 v[206:209], v185 offset:18432
	ds_read_b128 v[210:213], v185 offset:19456
	ds_read_b128 v[214:217], v185 offset:20480
	ds_read_b128 v[218:221], v185 offset:21504
	ds_read_b128 v[222:225], v185 offset:22528
	ds_read_b128 v[226:229], v185 offset:23552
	global_load_lds_dwordx4 v148, s[34:35]
	s_mov_b32 m0, s53
	s_nop 0
	global_load_lds_dwordx4 v146, s[34:35]
	s_barrier
	s_waitcnt lgkmcnt(0)
	v_mfma_f32_16x16x32_bf16 v[60:63], v[120:123], v[186:189], v[60:63]
	v_mfma_f32_16x16x32_bf16 v[56:59], v[132:135], v[186:189], v[56:59]
	v_mfma_f32_16x16x32_bf16 v[48:51], v[120:123], v[206:209], v[48:51]
	v_mfma_f32_16x16x32_bf16 v[40:43], v[132:135], v[206:209], v[40:43]
	v_mfma_f32_16x16x32_bf16 v[32:35], v[120:123], v[214:217], v[32:35]
	v_mfma_f32_16x16x32_bf16 v[24:27], v[132:135], v[214:217], v[24:27]
	v_mfma_f32_16x16x32_bf16 v[16:19], v[120:123], v[222:225], v[16:19]
	v_mfma_f32_16x16x32_bf16 v[8:11], v[132:135], v[222:225], v[8:11]
	v_mfma_f32_16x16x32_bf16 v[60:63], v[124:127], v[190:193], v[60:63]
	v_mfma_f32_16x16x32_bf16 v[56:59], v[136:139], v[190:193], v[56:59]
	v_mfma_f32_16x16x32_bf16 v[48:51], v[124:127], v[210:213], v[48:51]
	v_mfma_f32_16x16x32_bf16 v[40:43], v[136:139], v[210:213], v[40:43]
	v_mfma_f32_16x16x32_bf16 v[32:35], v[124:127], v[218:221], v[32:35]
	v_mfma_f32_16x16x32_bf16 v[24:27], v[136:139], v[218:221], v[24:27]
	v_mfma_f32_16x16x32_bf16 v[16:19], v[124:127], v[226:229], v[16:19]
	v_mfma_f32_16x16x32_bf16 v[8:11], v[136:139], v[226:229], v[8:11]
	s_barrier
	s_add_u32 s78, s22, 0x200000
	s_addc_u32 s79, s23, 0
	s_add_i32 s80, s80, s51
	s_mov_b32 m0, s80
	s_nop 0
	global_load_lds_dwordx4 v152, s[78:79]
	s_add_i32 m0, s80, 0x2000
	s_nop 0
	global_load_lds_dwordx4 v144, s[78:79]
	s_add_i32 s78, 0, 0x18000
	s_add_u32 s34, s34, 0x200000
	s_addc_u32 s35, s35, 0
	s_mov_b32 m0, s54
	s_waitcnt vmcnt(6)
	s_barrier
	v_mfma_f32_16x16x32_bf16 v[52:55], v[230:233], v[186:189], v[52:55]
	v_mfma_f32_16x16x32_bf16 v[44:47], v[238:241], v[186:189], v[44:47]
	v_mfma_f32_16x16x32_bf16 v[36:39], v[230:233], v[206:209], v[36:39]
	v_mfma_f32_16x16x32_bf16 v[28:31], v[238:241], v[206:209], v[28:31]
	v_mfma_f32_16x16x32_bf16 v[20:23], v[230:233], v[214:217], v[20:23]
	v_mfma_f32_16x16x32_bf16 v[12:15], v[238:241], v[214:217], v[12:15]
	v_mfma_f32_16x16x32_bf16 v[4:7], v[230:233], v[222:225], v[4:7]
	v_mfma_f32_16x16x32_bf16 v[0:3], v[238:241], v[222:225], v[0:3]
	v_mfma_f32_16x16x32_bf16 v[52:55], v[234:237], v[190:193], v[52:55]
	v_mfma_f32_16x16x32_bf16 v[44:47], v[242:245], v[190:193], v[44:47]
	v_mfma_f32_16x16x32_bf16 v[36:39], v[234:237], v[210:213], v[36:39]
	v_mfma_f32_16x16x32_bf16 v[28:31], v[242:245], v[210:213], v[28:31]
	v_mfma_f32_16x16x32_bf16 v[20:23], v[234:237], v[218:221], v[20:23]
	v_mfma_f32_16x16x32_bf16 v[12:15], v[242:245], v[218:221], v[12:15]
	v_mfma_f32_16x16x32_bf16 v[4:7], v[234:237], v[226:229], v[4:7]
	v_mfma_f32_16x16x32_bf16 v[0:3], v[242:245], v[226:229], v[0:3]
	s_barrier
	ds_read_b128 v[120:123], v250
	ds_read_b128 v[124:127], v250 offset:1024
	ds_read_b128 v[132:135], v250 offset:2048
	ds_read_b128 v[136:139], v250 offset:3072
	ds_read_b128 v[186:189], v185 offset:32768
	ds_read_b128 v[190:193], v185 offset:33792
	ds_read_b128 v[206:209], v185 offset:34816
	ds_read_b128 v[210:213], v185 offset:35840
	ds_read_b128 v[214:217], v185 offset:36864
	ds_read_b128 v[218:221], v185 offset:37888
	ds_read_b128 v[222:225], v185 offset:38912
	ds_read_b128 v[226:229], v185 offset:39936
	global_load_lds_dwordx4 v148, s[34:35]
	s_mov_b32 m0, s55
	s_nop 0
	global_load_lds_dwordx4 v146, s[34:35]
	s_waitcnt lgkmcnt(8)
	s_barrier
	s_waitcnt lgkmcnt(0)
	v_mfma_f32_16x16x32_bf16 v[140:143], v[120:123], v[186:189], v[140:143]
	v_mfma_f32_16x16x32_bf16 v[128:131], v[132:135], v[186:189], v[128:131]
	v_mfma_f32_16x16x32_bf16 v[112:115], v[120:123], v[206:209], v[112:115]
	v_mfma_f32_16x16x32_bf16 v[104:107], v[132:135], v[206:209], v[104:107]
	v_mfma_f32_16x16x32_bf16 v[96:99], v[120:123], v[214:217], v[96:99]
	v_mfma_f32_16x16x32_bf16 v[88:91], v[132:135], v[214:217], v[88:91]
	v_mfma_f32_16x16x32_bf16 v[80:83], v[120:123], v[222:225], v[80:83]
	v_mfma_f32_16x16x32_bf16 v[72:75], v[132:135], v[222:225], v[72:75]
	v_mfma_f32_16x16x32_bf16 v[140:143], v[124:127], v[190:193], v[140:143]
	v_mfma_f32_16x16x32_bf16 v[128:131], v[136:139], v[190:193], v[128:131]
	v_mfma_f32_16x16x32_bf16 v[112:115], v[124:127], v[210:213], v[112:115]
	v_mfma_f32_16x16x32_bf16 v[104:107], v[136:139], v[210:213], v[104:107]
	v_mfma_f32_16x16x32_bf16 v[96:99], v[124:127], v[218:221], v[96:99]
	v_mfma_f32_16x16x32_bf16 v[88:91], v[136:139], v[218:221], v[88:91]
	v_mfma_f32_16x16x32_bf16 v[80:83], v[124:127], v[226:229], v[80:83]
	v_mfma_f32_16x16x32_bf16 v[72:75], v[136:139], v[226:229], v[72:75]
	s_barrier
	s_add_i32 s34, 0, 0x1c000
	s_add_i32 s35, s78, s51
	s_add_u32 s100, s22, 0x80
	s_addc_u32 s101, s23, 0
	s_mov_b32 m0, s35
	ds_read_b128 v[230:233], v251
	ds_read_b128 v[234:237], v251 offset:1024
	ds_read_b128 v[238:241], v251 offset:2048
	ds_read_b128 v[242:245], v251 offset:3072
	global_load_lds_dwordx4 v152, s[100:101]
	s_add_i32 m0, s35, 0x2000
	s_nop 0
	global_load_lds_dwordx4 v144, s[100:101]
	s_barrier
	s_waitcnt lgkmcnt(0)
	v_mfma_f32_16x16x32_bf16 v[116:119], v[230:233], v[186:189], v[116:119]
	v_mfma_f32_16x16x32_bf16 v[108:111], v[238:241], v[186:189], v[108:111]
	v_mfma_f32_16x16x32_bf16 v[100:103], v[230:233], v[206:209], v[100:103]
	v_mfma_f32_16x16x32_bf16 v[92:95], v[238:241], v[206:209], v[92:95]
	v_mfma_f32_16x16x32_bf16 v[84:87], v[230:233], v[214:217], v[84:87]
	v_mfma_f32_16x16x32_bf16 v[76:79], v[238:241], v[214:217], v[76:79]
	v_mfma_f32_16x16x32_bf16 v[68:71], v[230:233], v[222:225], v[68:71]
	v_mfma_f32_16x16x32_bf16 v[64:67], v[238:241], v[222:225], v[64:67]
	v_mfma_f32_16x16x32_bf16 v[116:119], v[234:237], v[190:193], v[116:119]
	v_mfma_f32_16x16x32_bf16 v[108:111], v[242:245], v[190:193], v[108:111]
	v_mfma_f32_16x16x32_bf16 v[100:103], v[234:237], v[210:213], v[100:103]
	v_mfma_f32_16x16x32_bf16 v[92:95], v[242:245], v[210:213], v[92:95]
	v_mfma_f32_16x16x32_bf16 v[84:87], v[234:237], v[218:221], v[84:87]
	v_mfma_f32_16x16x32_bf16 v[76:79], v[242:245], v[218:221], v[76:79]
	v_mfma_f32_16x16x32_bf16 v[68:71], v[234:237], v[226:229], v[68:71]
	v_mfma_f32_16x16x32_bf16 v[64:67], v[242:245], v[226:229], v[64:67]
	s_barrier
	s_mov_b32 m0, s60
	ds_read_b128 v[186:189], v185 offset:49152
	ds_read_b128 v[190:193], v185 offset:50176
	ds_read_b128 v[206:209], v185 offset:51200
	ds_read_b128 v[210:213], v185 offset:52224
	ds_read_b128 v[214:217], v185 offset:53248
	ds_read_b128 v[218:221], v185 offset:54272
	ds_read_b128 v[222:225], v185 offset:55296
	ds_read_b128 v[226:229], v185 offset:56320
	global_load_lds_dwordx4 v148, s[98:99]
	s_mov_b32 m0, s61
	s_nop 0
	global_load_lds_dwordx4 v146, s[98:99]
	s_barrier
	s_waitcnt lgkmcnt(0)
	v_mfma_f32_16x16x32_bf16 v[60:63], v[120:123], v[186:189], v[60:63]
	v_mfma_f32_16x16x32_bf16 v[56:59], v[132:135], v[186:189], v[56:59]
	v_mfma_f32_16x16x32_bf16 v[48:51], v[120:123], v[206:209], v[48:51]
	v_mfma_f32_16x16x32_bf16 v[40:43], v[132:135], v[206:209], v[40:43]
	v_mfma_f32_16x16x32_bf16 v[32:35], v[120:123], v[214:217], v[32:35]
	v_mfma_f32_16x16x32_bf16 v[24:27], v[132:135], v[214:217], v[24:27]
	v_mfma_f32_16x16x32_bf16 v[16:19], v[120:123], v[222:225], v[16:19]
	v_mfma_f32_16x16x32_bf16 v[8:11], v[132:135], v[222:225], v[8:11]
	v_mfma_f32_16x16x32_bf16 v[60:63], v[124:127], v[190:193], v[60:63]
	v_mfma_f32_16x16x32_bf16 v[56:59], v[136:139], v[190:193], v[56:59]
	v_mfma_f32_16x16x32_bf16 v[48:51], v[124:127], v[210:213], v[48:51]
	v_mfma_f32_16x16x32_bf16 v[40:43], v[136:139], v[210:213], v[40:43]
	v_mfma_f32_16x16x32_bf16 v[32:35], v[124:127], v[218:221], v[32:35]
	v_mfma_f32_16x16x32_bf16 v[24:27], v[136:139], v[218:221], v[24:27]
	v_mfma_f32_16x16x32_bf16 v[16:19], v[124:127], v[226:229], v[16:19]
	v_mfma_f32_16x16x32_bf16 v[8:11], v[136:139], v[226:229], v[8:11]
	s_barrier
	s_add_u32 s22, s22, 0x200080
	s_addc_u32 s23, s23, 0
	s_add_i32 s34, s34, s51
	s_mov_b32 m0, s34
	s_nop 0
	global_load_lds_dwordx4 v152, s[22:23]
	s_add_i32 m0, s34, 0x2000
	s_nop 0
	global_load_lds_dwordx4 v144, s[22:23]
	s_add_i32 s69, s69, 2
	s_add_u32 s20, s20, 0x100
	s_addc_u32 s21, s21, 0
	s_add_u32 s63, s63, 0x100
	s_addc_u32 s68, s68, 0
	s_add_u32 s22, s20, 0xffe00080
	s_addc_u32 s23, s21, -1
	s_add_i32 s78, 0, 0x10000
	s_cmpk_eq_i32 s69, 0x7c
	s_cselect_b32 s35, s6, s23
	s_cselect_b32 s34, s7, s22
	s_cselect_b32 s23, s1, s68
	s_cselect_b32 s22, s17, s63
	s_add_i32 m0, s52, 0xc000
	s_cmpk_gt_u32 s69, 0x7d
	s_waitcnt vmcnt(6)
	s_barrier
	v_mfma_f32_16x16x32_bf16 v[52:55], v[230:233], v[186:189], v[52:55]
	v_mfma_f32_16x16x32_bf16 v[44:47], v[238:241], v[186:189], v[44:47]
	v_mfma_f32_16x16x32_bf16 v[36:39], v[230:233], v[206:209], v[36:39]
	v_mfma_f32_16x16x32_bf16 v[28:31], v[238:241], v[206:209], v[28:31]
	v_mfma_f32_16x16x32_bf16 v[20:23], v[230:233], v[214:217], v[20:23]
	v_mfma_f32_16x16x32_bf16 v[12:15], v[238:241], v[214:217], v[12:15]
	v_mfma_f32_16x16x32_bf16 v[4:7], v[230:233], v[222:225], v[4:7]
	v_mfma_f32_16x16x32_bf16 v[0:3], v[238:241], v[222:225], v[0:3]
	v_mfma_f32_16x16x32_bf16 v[52:55], v[234:237], v[190:193], v[52:55]
	v_mfma_f32_16x16x32_bf16 v[44:47], v[242:245], v[190:193], v[44:47]
	v_mfma_f32_16x16x32_bf16 v[36:39], v[234:237], v[210:213], v[36:39]
	v_mfma_f32_16x16x32_bf16 v[28:31], v[242:245], v[210:213], v[28:31]
	v_mfma_f32_16x16x32_bf16 v[20:23], v[234:237], v[218:221], v[20:23]
	v_mfma_f32_16x16x32_bf16 v[12:15], v[242:245], v[218:221], v[12:15]
	v_mfma_f32_16x16x32_bf16 v[4:7], v[234:237], v[226:229], v[4:7]
	v_mfma_f32_16x16x32_bf16 v[0:3], v[242:245], v[226:229], v[0:3]
	s_barrier
	s_cbranch_scc0 .LBB0_836
	v_readlane_b32 s98, v246, 0
	v_readlane_b32 s99, v246, 1
	s_cmp_eq_u32 s99, 0
	s_cbranch_scc1 .Lm2_epi
	s_and_b32 s100, s2, 0x7f
	s_lshl_b32 s100, s100, 18
	s_add_u32 s100, s100, 0x29800000
	s_add_u32 s100, s46, s100
	s_addc_u32 s101, s47, 0
	v_lshlrev_b32_e32 v186, 4, v182
	s_cmp_eq_u32 s99, 1
	s_cbranch_scc1 .Lm2_put_partial
	s_and_b32 s6, s2, 0x7f
	s_lshl_b32 s6, s6, 6
	s_add_u32 s6, s6, 0x2970a000
	s_add_u32 s6, s46, s6
	s_addc_u32 s7, s47, 0
	v_mov_b32_e32 v187, 0
	s_mov_b32 s99, 0
